# cache policy: P0 and HGRN inter-phase stores sc1 (write-through), GEMM1 epilogue stores sc1+nt
# speedup vs baseline: 1.0187x; 1.0039x over previous
; __device__ __forceinline__ float sigmoidf_(float x) { return __builtin_amdgcn_rcpf(1.f + __expf(-x)); }
;     __device__ __forceinline__ void operator()(const f32x4 (&acc)[2][2][4][2], const Unit& u, int wr, int wc, int fr, int fq) const {
;     ...
;             const int ti = u.pn >> 1, c0 = 128 * (ti >> 1) + 32 * wc + 8 * fq;
;             h16* dst = (ti & 1) ? PGG : PP;
; #pragma unroll
;             for (int ai = 0; ai < 2; ++ai)
; #pragma unroll
;                 for (int m = 0; m < 4; ++m) { const size_t off = (size_t)(row0 + ai * HALF + m * 16) * HW + c0;
;                     float o[8];
;                     if (ti & 1) {
; #pragma unroll
;                         for (int n = 0; n < 2; ++n)
; #pragma unroll
;                             for (int j = 0; j < 4; ++j) { const float g = acc[ai][1][m][n][j]; o[4 * n + j] = acc[ai][0][m][n][j] * g * sigmoidf_(g); }
;                     } else {
; #pragma unroll
;                         for (int n = 0; n < 2; ++n)
; #pragma unroll
;                             for (int j = 0; j < 4; ++j) o[4 * n + j] = acc[ai][0][m][n][j] * acc[ai][1][m][n][j];
;                     }
;                     u32x4 w; w.x = pkh(o[0], o[1]); w.y = pkh(o[2], o[3]); w.z = pkh(o[4], o[5]); w.w = pkh(o[6], o[7]);
;                     *(u32x4*)(dst + off) = w; }
.LBB0_109:
	s_and_b32 s27, s18, 0x7fffffc
	s_or_b32 s27, s27, s63
	s_and_b64 s[4:5], exec, s[4:5]
	s_cselect_b32 s4, s70, 0x26200000
	v_lshl_or_b32 v144, s27, 5, v159
	s_add_u32 s4, s4, s53
	s_addc_u32 s5, s7, 0
	v_ashrrev_i32_e32 v145, 31, v144
	v_ashrrev_i32_e32 v143, 31, v142
	v_lshl_add_u64 v[144:145], v[144:145], 1, s[4:5]
	v_cvt_pk_f16_f32 v147, v148, v149
	v_cvt_pk_f16_f32 v149, v150, v151
	v_lshlrev_b64 v[150:151], 12, v[142:143]
	v_cvt_pk_f16_f32 v146, v152, v153
	v_cvt_pk_f16_f32 v148, v154, v155
	v_lshl_add_u64 v[150:151], v[144:145], 0, v[150:151]
	global_store_dwordx4 v[150:151], v[146:149], off sc1 nt
	s_mov_b64 s[48:49], -1
	s_andn2_b64 vcc, exec, s[46:47]
	v_cndmask_b32_e64 v146, 0, 1, s[46:47]
	v_cmp_ne_u32_e64 s[4:5], 1, v146
	v_pk_mul_f32 v[148:149], v[116:117], v[92:93]
	v_pk_mul_f32 v[146:147], v[112:113], v[88:89]
	s_cbranch_vccnz .LBB0_111
	v_mul_f32_e32 v151, 0xbfb8aa3b, v93
	v_exp_f32_e32 v151, v151
	v_mul_f32_e32 v153, 0xbfb8aa3b, v95
	v_exp_f32_e32 v154, v153
	v_mul_f32_e32 v150, 0xbfb8aa3b, v92
	v_add_f32_e32 v151, 1.0, v151
	v_rcp_f32_e32 v153, v151
	v_add_f32_e32 v151, 1.0, v154
	v_mul_f32_e32 v154, 0xbfb8aa3b, v88
	v_exp_f32_e32 v154, v154
	v_mul_f32_e32 v155, 0xbfb8aa3b, v89
	v_exp_f32_e32 v150, v150
	v_exp_f32_e32 v155, v155
	v_add_f32_e32 v154, 1.0, v154
	v_rcp_f32_e32 v156, v154
	v_add_f32_e32 v150, 1.0, v150
	v_add_f32_e32 v154, 1.0, v155
	v_mul_f32_e32 v155, 0xbfb8aa3b, v90
	v_rcp_f32_e32 v152, v150
	v_mul_f32_e32 v150, 0xbfb8aa3b, v94
	v_exp_f32_e32 v155, v155
	v_mul_f32_e32 v157, 0xbfb8aa3b, v91
	v_exp_f32_e32 v150, v150
	v_exp_f32_e32 v165, v157
	v_rcp_f32_e32 v157, v154
	v_add_f32_e32 v154, 1.0, v155
	v_add_f32_e32 v150, 1.0, v150
	v_rcp_f32_e32 v164, v154
	v_add_f32_e32 v154, 1.0, v165
	v_rcp_f32_e32 v150, v150
	v_rcp_f32_e32 v151, v151
	v_rcp_f32_e32 v165, v154
	v_pk_mul_f32 v[154:155], v[118:119], v[94:95]
	v_pk_mul_f32 v[166:167], v[114:115], v[90:91]
	v_pk_mul_f32 v[150:151], v[154:155], v[150:151]
	v_pk_mul_f32 v[154:155], v[148:149], v[152:153]
	v_pk_mul_f32 v[152:153], v[166:167], v[164:165]
	v_pk_mul_f32 v[156:157], v[146:147], v[156:157]
	s_mov_b64 s[48:49], 0

; __device__ __forceinline__ float sigmoidf_(float x) { return __builtin_amdgcn_rcpf(1.f + __expf(-x)); }
;     __device__ __forceinline__ void operator()(const f32x4 (&acc)[2][2][4][2], const Unit& u, int wr, int wc, int fr, int fq) const {
;     ...
;             for (int ai = 0; ai < 2; ++ai)
; #pragma unroll
;                 for (int m = 0; m < 4; ++m) { const size_t off = (size_t)(row0 + ai * HALF + m * 16) * HW + c0;
;                     float o[8];
;                     if (ti & 1) {
; #pragma unroll
;                         for (int n = 0; n < 2; ++n)
; #pragma unroll
;                             for (int j = 0; j < 4; ++j) { const float g = acc[ai][1][m][n][j]; o[4 * n + j] = acc[ai][0][m][n][j] * g * sigmoidf_(g); }
;                     } else {
; #pragma unroll
;                         for (int n = 0; n < 2; ++n)
; #pragma unroll
;                             for (int j = 0; j < 4; ++j) o[4 * n + j] = acc[ai][0][m][n][j] * acc[ai][1][m][n][j];
;                     }
;                     u32x4 w; w.x = pkh(o[0], o[1]); w.y = pkh(o[2], o[3]); w.z = pkh(o[4], o[5]); w.w = pkh(o[6], o[7]);
;                     *(u32x4*)(dst + off) = w; }
.LBB0_113:
	v_or_b32_e32 v164, 16, v142
	v_ashrrev_i32_e32 v165, 31, v164
	v_cvt_pk_f16_f32 v147, v150, v151
	v_lshlrev_b64 v[150:151], 12, v[164:165]
	v_cvt_pk_f16_f32 v146, v154, v155
	v_cvt_pk_f16_f32 v148, v156, v157
	v_cvt_pk_f16_f32 v149, v152, v153
	v_lshl_add_u64 v[150:151], v[144:145], 0, v[150:151]
	global_store_dwordx4 v[150:151], v[146:149], off sc1 nt
	s_mov_b64 s[46:47], -1
	s_and_b64 vcc, exec, s[4:5]
	v_pk_mul_f32 v[148:149], v[100:101], v[76:77]
	v_pk_mul_f32 v[146:147], v[96:97], v[72:73]
	s_cbranch_vccnz .LBB0_115
	v_mul_f32_e32 v151, 0xbfb8aa3b, v77
	v_exp_f32_e32 v151, v151
	v_mul_f32_e32 v153, 0xbfb8aa3b, v79
	v_exp_f32_e32 v154, v153
	v_mul_f32_e32 v150, 0xbfb8aa3b, v76
	v_add_f32_e32 v151, 1.0, v151
	v_rcp_f32_e32 v153, v151
	v_add_f32_e32 v151, 1.0, v154
	v_mul_f32_e32 v154, 0xbfb8aa3b, v72
	v_exp_f32_e32 v154, v154
	v_mul_f32_e32 v155, 0xbfb8aa3b, v73
	v_exp_f32_e32 v150, v150
	v_exp_f32_e32 v155, v155
	v_add_f32_e32 v154, 1.0, v154
	v_rcp_f32_e32 v156, v154
	v_add_f32_e32 v150, 1.0, v150
	v_add_f32_e32 v154, 1.0, v155
	v_mul_f32_e32 v155, 0xbfb8aa3b, v74
	v_rcp_f32_e32 v152, v150
	v_mul_f32_e32 v150, 0xbfb8aa3b, v78
	v_exp_f32_e32 v155, v155
	v_mul_f32_e32 v157, 0xbfb8aa3b, v75
	v_exp_f32_e32 v150, v150
	v_exp_f32_e32 v165, v157
	v_rcp_f32_e32 v157, v154
	v_add_f32_e32 v154, 1.0, v155
	v_add_f32_e32 v150, 1.0, v150
	v_rcp_f32_e32 v164, v154
	v_add_f32_e32 v154, 1.0, v165
	v_rcp_f32_e32 v150, v150
	v_rcp_f32_e32 v151, v151
	v_rcp_f32_e32 v165, v154
	v_pk_mul_f32 v[154:155], v[102:103], v[78:79]
	v_pk_mul_f32 v[166:167], v[98:99], v[74:75]
	v_pk_mul_f32 v[150:151], v[154:155], v[150:151]
	v_pk_mul_f32 v[154:155], v[148:149], v[152:153]
	v_pk_mul_f32 v[152:153], v[166:167], v[164:165]
	v_pk_mul_f32 v[156:157], v[146:147], v[156:157]
	s_mov_b64 s[46:47], 0

; __device__ __forceinline__ float sigmoidf_(float x) { return __builtin_amdgcn_rcpf(1.f + __expf(-x)); }
;     __device__ __forceinline__ void operator()(const f32x4 (&acc)[2][2][4][2], const Unit& u, int wr, int wc, int fr, int fq) const {
;     ...
;             for (int ai = 0; ai < 2; ++ai)
; #pragma unroll
;                 for (int m = 0; m < 4; ++m) { const size_t off = (size_t)(row0 + ai * HALF + m * 16) * HW + c0;
;                     float o[8];
;                     if (ti & 1) {
; #pragma unroll
;                         for (int n = 0; n < 2; ++n)
; #pragma unroll
;                             for (int j = 0; j < 4; ++j) { const float g = acc[ai][1][m][n][j]; o[4 * n + j] = acc[ai][0][m][n][j] * g * sigmoidf_(g); }
;                     } else {
; #pragma unroll
;                         for (int n = 0; n < 2; ++n)
; #pragma unroll
;                             for (int j = 0; j < 4; ++j) o[4 * n + j] = acc[ai][0][m][n][j] * acc[ai][1][m][n][j];
;                     }
;                     u32x4 w; w.x = pkh(o[0], o[1]); w.y = pkh(o[2], o[3]); w.z = pkh(o[4], o[5]); w.w = pkh(o[6], o[7]);
;                     *(u32x4*)(dst + off) = w; }
.LBB0_117:
	v_or_b32_e32 v164, 32, v142
	v_ashrrev_i32_e32 v165, 31, v164
	v_cvt_pk_f16_f32 v147, v150, v151
	v_lshlrev_b64 v[150:151], 12, v[164:165]
	v_cvt_pk_f16_f32 v146, v154, v155
	v_cvt_pk_f16_f32 v148, v156, v157
	v_cvt_pk_f16_f32 v149, v152, v153
	v_lshl_add_u64 v[150:151], v[144:145], 0, v[150:151]
	global_store_dwordx4 v[150:151], v[146:149], off sc1 nt
	s_mov_b64 s[46:47], -1
	s_and_b64 vcc, exec, s[4:5]
	v_pk_mul_f32 v[148:149], v[84:85], v[68:69]
	v_pk_mul_f32 v[146:147], v[80:81], v[64:65]
	s_cbranch_vccnz .LBB0_119
	v_mul_f32_e32 v151, 0xbfb8aa3b, v69
	v_exp_f32_e32 v151, v151
	v_mul_f32_e32 v153, 0xbfb8aa3b, v71
	v_exp_f32_e32 v154, v153
	v_mul_f32_e32 v150, 0xbfb8aa3b, v68
	v_add_f32_e32 v151, 1.0, v151
	v_rcp_f32_e32 v153, v151
	v_add_f32_e32 v151, 1.0, v154
	v_mul_f32_e32 v154, 0xbfb8aa3b, v64
	v_exp_f32_e32 v154, v154
	v_mul_f32_e32 v155, 0xbfb8aa3b, v65
	v_exp_f32_e32 v150, v150
	v_exp_f32_e32 v155, v155
	v_add_f32_e32 v154, 1.0, v154
	v_rcp_f32_e32 v156, v154
	v_add_f32_e32 v150, 1.0, v150
	v_add_f32_e32 v154, 1.0, v155
	v_mul_f32_e32 v155, 0xbfb8aa3b, v66
	v_rcp_f32_e32 v152, v150
	v_mul_f32_e32 v150, 0xbfb8aa3b, v70
	v_exp_f32_e32 v155, v155
	v_mul_f32_e32 v157, 0xbfb8aa3b, v67
	v_exp_f32_e32 v150, v150
	v_exp_f32_e32 v165, v157
	v_rcp_f32_e32 v157, v154
	v_add_f32_e32 v154, 1.0, v155
	v_add_f32_e32 v150, 1.0, v150
	v_rcp_f32_e32 v164, v154
	v_add_f32_e32 v154, 1.0, v165
	v_rcp_f32_e32 v150, v150
	v_rcp_f32_e32 v151, v151
	v_rcp_f32_e32 v165, v154
	v_pk_mul_f32 v[154:155], v[86:87], v[70:71]
	v_pk_mul_f32 v[166:167], v[82:83], v[66:67]
	v_pk_mul_f32 v[150:151], v[154:155], v[150:151]
	v_pk_mul_f32 v[154:155], v[148:149], v[152:153]
	v_pk_mul_f32 v[152:153], v[166:167], v[164:165]
	v_pk_mul_f32 v[156:157], v[146:147], v[156:157]
	s_mov_b64 s[46:47], 0

; __device__ __forceinline__ float sigmoidf_(float x) { return __builtin_amdgcn_rcpf(1.f + __expf(-x)); }
;     __device__ __forceinline__ void operator()(const f32x4 (&acc)[2][2][4][2], const Unit& u, int wr, int wc, int fr, int fq) const {
;     ...
;             for (int ai = 0; ai < 2; ++ai)
; #pragma unroll
;                 for (int m = 0; m < 4; ++m) { const size_t off = (size_t)(row0 + ai * HALF + m * 16) * HW + c0;
;                     float o[8];
;                     if (ti & 1) {
; #pragma unroll
;                         for (int n = 0; n < 2; ++n)
; #pragma unroll
;                             for (int j = 0; j < 4; ++j) { const float g = acc[ai][1][m][n][j]; o[4 * n + j] = acc[ai][0][m][n][j] * g * sigmoidf_(g); }
;                     } else {
; #pragma unroll
;                         for (int n = 0; n < 2; ++n)
; #pragma unroll
;                             for (int j = 0; j < 4; ++j) o[4 * n + j] = acc[ai][0][m][n][j] * acc[ai][1][m][n][j];
;                     }
;                     u32x4 w; w.x = pkh(o[0], o[1]); w.y = pkh(o[2], o[3]); w.z = pkh(o[4], o[5]); w.w = pkh(o[6], o[7]);
;                     *(u32x4*)(dst + off) = w; }
.LBB0_121:
	v_or_b32_e32 v164, 48, v142
	v_ashrrev_i32_e32 v165, 31, v164
	v_cvt_pk_f16_f32 v147, v150, v151
	v_lshlrev_b64 v[150:151], 12, v[164:165]
	v_cvt_pk_f16_f32 v146, v154, v155
	v_cvt_pk_f16_f32 v148, v156, v157
	v_cvt_pk_f16_f32 v149, v152, v153
	v_lshl_add_u64 v[150:151], v[144:145], 0, v[150:151]
	global_store_dwordx4 v[150:151], v[146:149], off sc1 nt
	s_mov_b64 s[46:47], -1
	s_and_b64 vcc, exec, s[4:5]
	v_pk_mul_f32 v[148:149], v[60:61], v[44:45]
	v_pk_mul_f32 v[146:147], v[56:57], v[40:41]
	s_cbranch_vccnz .LBB0_123
	v_mul_f32_e32 v151, 0xbfb8aa3b, v45
	v_exp_f32_e32 v151, v151
	v_mul_f32_e32 v153, 0xbfb8aa3b, v47
	v_exp_f32_e32 v154, v153
	v_mul_f32_e32 v150, 0xbfb8aa3b, v44
	v_add_f32_e32 v151, 1.0, v151
	v_rcp_f32_e32 v153, v151
	v_add_f32_e32 v151, 1.0, v154
	v_mul_f32_e32 v154, 0xbfb8aa3b, v40
	v_exp_f32_e32 v154, v154
	v_mul_f32_e32 v155, 0xbfb8aa3b, v41
	v_exp_f32_e32 v150, v150
	v_exp_f32_e32 v155, v155
	v_add_f32_e32 v154, 1.0, v154
	v_rcp_f32_e32 v156, v154
	v_add_f32_e32 v150, 1.0, v150
	v_add_f32_e32 v154, 1.0, v155
	v_mul_f32_e32 v155, 0xbfb8aa3b, v42
	v_rcp_f32_e32 v152, v150
	v_mul_f32_e32 v150, 0xbfb8aa3b, v46
	v_exp_f32_e32 v155, v155
	v_mul_f32_e32 v157, 0xbfb8aa3b, v43
	v_exp_f32_e32 v150, v150
	v_exp_f32_e32 v165, v157
	v_rcp_f32_e32 v157, v154
	v_add_f32_e32 v154, 1.0, v155
	v_add_f32_e32 v150, 1.0, v150
	v_rcp_f32_e32 v164, v154
	v_add_f32_e32 v154, 1.0, v165
	v_rcp_f32_e32 v150, v150
	v_rcp_f32_e32 v151, v151
	v_rcp_f32_e32 v165, v154
	v_pk_mul_f32 v[154:155], v[62:63], v[46:47]
	v_pk_mul_f32 v[166:167], v[58:59], v[42:43]
	v_pk_mul_f32 v[150:151], v[154:155], v[150:151]
	v_pk_mul_f32 v[154:155], v[148:149], v[152:153]
	v_pk_mul_f32 v[152:153], v[166:167], v[164:165]
	v_pk_mul_f32 v[156:157], v[146:147], v[156:157]
	s_mov_b64 s[46:47], 0

; __device__ __forceinline__ float sigmoidf_(float x) { return __builtin_amdgcn_rcpf(1.f + __expf(-x)); }
;     __device__ __forceinline__ void operator()(const f32x4 (&acc)[2][2][4][2], const Unit& u, int wr, int wc, int fr, int fq) const {
;     ...
;             for (int ai = 0; ai < 2; ++ai)
; #pragma unroll
;                 for (int m = 0; m < 4; ++m) { const size_t off = (size_t)(row0 + ai * HALF + m * 16) * HW + c0;
;                     float o[8];
;                     if (ti & 1) {
; #pragma unroll
;                         for (int n = 0; n < 2; ++n)
; #pragma unroll
;                             for (int j = 0; j < 4; ++j) { const float g = acc[ai][1][m][n][j]; o[4 * n + j] = acc[ai][0][m][n][j] * g * sigmoidf_(g); }
;                     } else {
; #pragma unroll
;                         for (int n = 0; n < 2; ++n)
; #pragma unroll
;                             for (int j = 0; j < 4; ++j) o[4 * n + j] = acc[ai][0][m][n][j] * acc[ai][1][m][n][j];
;                     }
;                     u32x4 w; w.x = pkh(o[0], o[1]); w.y = pkh(o[2], o[3]); w.z = pkh(o[4], o[5]); w.w = pkh(o[6], o[7]);
;                     *(u32x4*)(dst + off) = w; }
.LBB0_125:
	v_lshlrev_b64 v[164:165], 12, v[142:143]
	v_cvt_pk_f16_f32 v147, v150, v151
	v_lshl_add_u64 v[150:151], v[144:145], 0, v[164:165]
	v_add_co_u32_e32 v150, vcc, 0x80000, v150
	v_cvt_pk_f16_f32 v146, v154, v155
	v_cvt_pk_f16_f32 v148, v156, v157
	v_cvt_pk_f16_f32 v149, v152, v153
	v_addc_co_u32_e32 v151, vcc, 0, v151, vcc
	global_store_dwordx4 v[150:151], v[146:149], off sc1 nt
	s_mov_b64 s[46:47], -1
	s_and_b64 vcc, exec, s[4:5]
	v_pk_mul_f32 v[148:149], v[52:53], v[28:29]
	v_pk_mul_f32 v[146:147], v[48:49], v[24:25]
	s_cbranch_vccnz .LBB0_127
	v_mul_f32_e32 v151, 0xbfb8aa3b, v29
	v_exp_f32_e32 v151, v151
	v_mul_f32_e32 v153, 0xbfb8aa3b, v31
	v_exp_f32_e32 v154, v153
	v_mul_f32_e32 v150, 0xbfb8aa3b, v28
	v_add_f32_e32 v151, 1.0, v151
	v_rcp_f32_e32 v153, v151
	v_add_f32_e32 v151, 1.0, v154
	v_mul_f32_e32 v154, 0xbfb8aa3b, v24
	v_exp_f32_e32 v154, v154
	v_mul_f32_e32 v155, 0xbfb8aa3b, v25
	v_exp_f32_e32 v150, v150
	v_exp_f32_e32 v155, v155
	v_add_f32_e32 v154, 1.0, v154
	v_rcp_f32_e32 v156, v154
	v_add_f32_e32 v150, 1.0, v150
	v_add_f32_e32 v154, 1.0, v155
	v_mul_f32_e32 v155, 0xbfb8aa3b, v26
	v_rcp_f32_e32 v152, v150
	v_mul_f32_e32 v150, 0xbfb8aa3b, v30
	v_exp_f32_e32 v155, v155
	v_mul_f32_e32 v157, 0xbfb8aa3b, v27
	v_exp_f32_e32 v150, v150
	v_exp_f32_e32 v165, v157
	v_rcp_f32_e32 v157, v154
	v_add_f32_e32 v154, 1.0, v155
	v_add_f32_e32 v150, 1.0, v150
	v_rcp_f32_e32 v164, v154
	v_add_f32_e32 v154, 1.0, v165
	v_rcp_f32_e32 v150, v150
	v_rcp_f32_e32 v151, v151
	v_rcp_f32_e32 v165, v154
	v_pk_mul_f32 v[154:155], v[54:55], v[30:31]
	v_pk_mul_f32 v[166:167], v[50:51], v[26:27]
	v_pk_mul_f32 v[150:151], v[154:155], v[150:151]
	v_pk_mul_f32 v[154:155], v[148:149], v[152:153]
	v_pk_mul_f32 v[152:153], v[166:167], v[164:165]
	v_pk_mul_f32 v[156:157], v[146:147], v[156:157]
	s_mov_b64 s[46:47], 0

; __device__ __forceinline__ float sigmoidf_(float x) { return __builtin_amdgcn_rcpf(1.f + __expf(-x)); }
;     __device__ __forceinline__ void operator()(const f32x4 (&acc)[2][2][4][2], const Unit& u, int wr, int wc, int fr, int fq) const {
;     ...
;             for (int ai = 0; ai < 2; ++ai)
; #pragma unroll
;                 for (int m = 0; m < 4; ++m) { const size_t off = (size_t)(row0 + ai * HALF + m * 16) * HW + c0;
;                     float o[8];
;                     if (ti & 1) {
; #pragma unroll
;                         for (int n = 0; n < 2; ++n)
; #pragma unroll
;                             for (int j = 0; j < 4; ++j) { const float g = acc[ai][1][m][n][j]; o[4 * n + j] = acc[ai][0][m][n][j] * g * sigmoidf_(g); }
;                     } else {
; #pragma unroll
;                         for (int n = 0; n < 2; ++n)
; #pragma unroll
;                             for (int j = 0; j < 4; ++j) o[4 * n + j] = acc[ai][0][m][n][j] * acc[ai][1][m][n][j];
;                     }
;                     u32x4 w; w.x = pkh(o[0], o[1]); w.y = pkh(o[2], o[3]); w.z = pkh(o[4], o[5]); w.w = pkh(o[6], o[7]);
;                     *(u32x4*)(dst + off) = w; }
.LBB0_129:
	v_lshlrev_b64 v[164:165], 12, v[142:143]
	v_cvt_pk_f16_f32 v147, v150, v151
	v_lshl_add_u64 v[150:151], v[144:145], 0, v[164:165]
	v_add_co_u32_e32 v150, vcc, 0x90000, v150
	v_cvt_pk_f16_f32 v146, v154, v155
	v_cvt_pk_f16_f32 v148, v156, v157
	v_cvt_pk_f16_f32 v149, v152, v153
	v_addc_co_u32_e32 v151, vcc, 0, v151, vcc
	global_store_dwordx4 v[150:151], v[146:149], off sc1 nt
	s_mov_b64 s[46:47], -1
	s_and_b64 vcc, exec, s[4:5]
	v_pk_mul_f32 v[148:149], v[36:37], v[12:13]
	v_pk_mul_f32 v[146:147], v[32:33], v[8:9]
	s_cbranch_vccnz .LBB0_131
	v_mul_f32_e32 v151, 0xbfb8aa3b, v13
	v_exp_f32_e32 v151, v151
	v_mul_f32_e32 v153, 0xbfb8aa3b, v15
	v_exp_f32_e32 v154, v153
	v_mul_f32_e32 v150, 0xbfb8aa3b, v12
	v_add_f32_e32 v151, 1.0, v151
	v_rcp_f32_e32 v153, v151
	v_add_f32_e32 v151, 1.0, v154
	v_mul_f32_e32 v154, 0xbfb8aa3b, v8
	v_exp_f32_e32 v154, v154
	v_mul_f32_e32 v155, 0xbfb8aa3b, v9
	v_exp_f32_e32 v150, v150
	v_exp_f32_e32 v155, v155
	v_add_f32_e32 v154, 1.0, v154
	v_rcp_f32_e32 v156, v154
	v_add_f32_e32 v150, 1.0, v150
	v_add_f32_e32 v154, 1.0, v155
	v_mul_f32_e32 v155, 0xbfb8aa3b, v10
	v_rcp_f32_e32 v152, v150
	v_mul_f32_e32 v150, 0xbfb8aa3b, v14
	v_exp_f32_e32 v155, v155
	v_mul_f32_e32 v157, 0xbfb8aa3b, v11
	v_exp_f32_e32 v150, v150
	v_exp_f32_e32 v165, v157
	v_rcp_f32_e32 v157, v154
	v_add_f32_e32 v154, 1.0, v155
	v_add_f32_e32 v150, 1.0, v150
	v_rcp_f32_e32 v164, v154
	v_add_f32_e32 v154, 1.0, v165
	v_rcp_f32_e32 v150, v150
	v_rcp_f32_e32 v151, v151
	v_rcp_f32_e32 v165, v154
	v_pk_mul_f32 v[154:155], v[38:39], v[14:15]
	v_pk_mul_f32 v[166:167], v[34:35], v[10:11]
	v_pk_mul_f32 v[150:151], v[154:155], v[150:151]
	v_pk_mul_f32 v[154:155], v[148:149], v[152:153]
	v_pk_mul_f32 v[152:153], v[166:167], v[164:165]
	v_pk_mul_f32 v[156:157], v[146:147], v[156:157]
	s_mov_b64 s[46:47], 0

; __device__ __forceinline__ float sigmoidf_(float x) { return __builtin_amdgcn_rcpf(1.f + __expf(-x)); }
;     __device__ __forceinline__ void operator()(const f32x4 (&acc)[2][2][4][2], const Unit& u, int wr, int wc, int fr, int fq) const {
;     ...
;             for (int ai = 0; ai < 2; ++ai)
; #pragma unroll
;                 for (int m = 0; m < 4; ++m) { const size_t off = (size_t)(row0 + ai * HALF + m * 16) * HW + c0;
;                     float o[8];
;                     if (ti & 1) {
; #pragma unroll
;                         for (int n = 0; n < 2; ++n)
; #pragma unroll
;                             for (int j = 0; j < 4; ++j) { const float g = acc[ai][1][m][n][j]; o[4 * n + j] = acc[ai][0][m][n][j] * g * sigmoidf_(g); }
;                     } else {
; #pragma unroll
;                         for (int n = 0; n < 2; ++n)
; #pragma unroll
;                             for (int j = 0; j < 4; ++j) o[4 * n + j] = acc[ai][0][m][n][j] * acc[ai][1][m][n][j];
;                     }
;                     u32x4 w; w.x = pkh(o[0], o[1]); w.y = pkh(o[2], o[3]); w.z = pkh(o[4], o[5]); w.w = pkh(o[6], o[7]);
;                     *(u32x4*)(dst + off) = w; }
.LBB0_133:
	v_lshlrev_b64 v[164:165], 12, v[142:143]
	v_cvt_pk_f16_f32 v147, v150, v151
	v_lshl_add_u64 v[150:151], v[144:145], 0, v[164:165]
	v_add_co_u32_e32 v150, vcc, 0xa0000, v150
	v_cvt_pk_f16_f32 v146, v154, v155
	v_cvt_pk_f16_f32 v148, v156, v157
	v_cvt_pk_f16_f32 v149, v152, v153
	v_addc_co_u32_e32 v151, vcc, 0, v151, vcc
	global_store_dwordx4 v[150:151], v[146:149], off sc1 nt
	s_mov_b64 s[46:47], -1
	s_and_b64 vcc, exec, s[4:5]
	v_pk_mul_f32 v[148:149], v[20:21], v[4:5]
	v_pk_mul_f32 v[146:147], v[16:17], v[0:1]
	s_cbranch_vccnz .LBB0_135
	v_mul_f32_e32 v151, 0xbfb8aa3b, v5
	v_exp_f32_e32 v151, v151
	v_mul_f32_e32 v153, 0xbfb8aa3b, v7
	v_exp_f32_e32 v154, v153
	v_mul_f32_e32 v150, 0xbfb8aa3b, v4
	v_add_f32_e32 v151, 1.0, v151
	v_rcp_f32_e32 v153, v151
	v_add_f32_e32 v151, 1.0, v154
	v_mul_f32_e32 v154, 0xbfb8aa3b, v0
	v_exp_f32_e32 v154, v154
	v_mul_f32_e32 v155, 0xbfb8aa3b, v1
	v_exp_f32_e32 v150, v150
	v_exp_f32_e32 v155, v155
	v_add_f32_e32 v154, 1.0, v154
	v_rcp_f32_e32 v156, v154
	v_add_f32_e32 v150, 1.0, v150
	v_add_f32_e32 v154, 1.0, v155
	v_mul_f32_e32 v155, 0xbfb8aa3b, v2
	v_rcp_f32_e32 v152, v150
	v_mul_f32_e32 v150, 0xbfb8aa3b, v6
	v_exp_f32_e32 v155, v155
	v_mul_f32_e32 v157, 0xbfb8aa3b, v3
	v_exp_f32_e32 v150, v150
	v_exp_f32_e32 v165, v157
	v_rcp_f32_e32 v157, v154
	v_add_f32_e32 v154, 1.0, v155
	v_add_f32_e32 v150, 1.0, v150
	v_rcp_f32_e32 v164, v154
	v_add_f32_e32 v154, 1.0, v165
	v_rcp_f32_e32 v150, v150
	v_rcp_f32_e32 v151, v151
	v_rcp_f32_e32 v165, v154
	v_pk_mul_f32 v[154:155], v[22:23], v[6:7]
	v_pk_mul_f32 v[166:167], v[18:19], v[2:3]
	v_pk_mul_f32 v[150:151], v[154:155], v[150:151]
	v_pk_mul_f32 v[154:155], v[148:149], v[152:153]
	v_pk_mul_f32 v[152:153], v[166:167], v[164:165]
	v_pk_mul_f32 v[156:157], v[146:147], v[156:157]
	s_mov_b64 s[46:47], 0

; __device__ __forceinline__ float sigmoidf_(float x) { return __builtin_amdgcn_rcpf(1.f + __expf(-x)); }
;     __device__ __forceinline__ void operator()(const f32x4 (&acc)[2][2][4][2], const Unit& u, int wr, int wc, int fr, int fq) const {
;     ...
;             for (int ai = 0; ai < 2; ++ai)
; #pragma unroll
;                 for (int m = 0; m < 4; ++m) { const size_t off = (size_t)(row0 + ai * HALF + m * 16) * HW + c0;
;                     float o[8];
;                     if (ti & 1) {
; #pragma unroll
;                         for (int n = 0; n < 2; ++n)
; #pragma unroll
;                             for (int j = 0; j < 4; ++j) { const float g = acc[ai][1][m][n][j]; o[4 * n + j] = acc[ai][0][m][n][j] * g * sigmoidf_(g); }
;                     } else {
; #pragma unroll
;                         for (int n = 0; n < 2; ++n)
; #pragma unroll
;                             for (int j = 0; j < 4; ++j) o[4 * n + j] = acc[ai][0][m][n][j] * acc[ai][1][m][n][j];
;                     }
;                     u32x4 w; w.x = pkh(o[0], o[1]); w.y = pkh(o[2], o[3]); w.z = pkh(o[4], o[5]); w.w = pkh(o[6], o[7]);
;                     *(u32x4*)(dst + off) = w; }
.LBB0_137:
	v_lshlrev_b64 v[164:165], 12, v[142:143]
	v_lshl_add_u64 v[144:145], v[144:145], 0, v[164:165]
	v_add_co_u32_e32 v144, vcc, 0xb0000, v144
	v_cvt_pk_f16_f32 v146, v154, v155
	v_cvt_pk_f16_f32 v147, v150, v151
	v_cvt_pk_f16_f32 v148, v156, v157
	v_cvt_pk_f16_f32 v149, v152, v153
	v_addc_co_u32_e32 v145, vcc, 0, v145, vcc
	global_store_dwordx4 v[144:145], v[146:149], off sc1 nt

;     __device__ __forceinline__ void operator()(const f32x4 (&acc)[2][2][4][2], const Unit& u, int wr, int wc, int fr, int fq) const {
;     ...
;         if ((u.pn & 1) == 0) {
;             h16* base = PA + 256 * (u.pn >> 1) + wc * 32 + 8 * fq;
; #pragma unroll
;             for (int ai = 0; ai < 2; ++ai)
; #pragma unroll
;                 for (int m = 0; m < 4; ++m) { h16* rowp = base + (size_t)(row0 + ai * HALF + m * 16) * 8192;
; #pragma unroll
;                     for (int bj = 0; bj < 2; ++bj) { const f32x4 v0 = acc[ai][bj][m][0], v1 = acc[ai][bj][m][1];
;                         u32x4 w; w.x = pkh(v0[0], v0[1]); w.y = pkh(v0[2], v0[3]); w.z = pkh(v1[0], v1[1]); w.w = pkh(v1[2], v1[3]);
;                         *(u32x4*)(rowp + bj * HALF) = w; } }
.LBB0_139:
	s_and_b64 vcc, exec, s[4:5]
	s_cbranch_vccz .LBB0_138
	s_lshl_b32 s4, s18, 7
	s_ashr_i32 s5, s4, 31
	v_ashrrev_i32_e32 v143, 31, v142
	v_lshl_add_u64 v[144:145], s[4:5], 1, v[132:133]
	v_lshlrev_b64 v[146:147], 14, v[142:143]
	v_lshl_add_u64 v[146:147], v[144:145], 0, v[146:147]
	v_cvt_pk_f16_f32 v60, v60, v61
	v_cvt_pk_f16_f32 v61, v62, v63
	v_cvt_pk_f16_f32 v62, v56, v57
	v_add_co_u32_e32 v56, vcc, s71, v146
	v_cvt_pk_f16_f32 v68, v68, v69
	v_cvt_pk_f16_f32 v69, v70, v71
	v_cvt_pk_f16_f32 v70, v64, v65
	v_lshl_add_u64 v[64:65], v[146:147], 0, s[10:11]
	v_addc_co_u32_e32 v57, vcc, 0, v147, vcc
	v_cvt_pk_f16_f32 v44, v44, v45
	v_cvt_pk_f16_f32 v45, v46, v47
	v_cvt_pk_f16_f32 v46, v40, v41
	v_cvt_pk_f16_f32 v47, v42, v43
	v_cvt_pk_f16_f32 v108, v108, v109
	v_cvt_pk_f16_f32 v109, v110, v111
	v_cvt_pk_f16_f32 v110, v104, v105
	v_or_b32_e32 v104, 16, v142
	global_store_dwordx4 v[64:65], v[44:47], off offset:256 sc1 nt
	v_ashrrev_i32_e32 v105, 31, v104
	v_cvt_pk_f16_f32 v92, v92, v93
	v_add_co_u32_e32 v46, vcc, s72, v146
	v_cvt_pk_f16_f32 v93, v94, v95
	v_cvt_pk_f16_f32 v94, v88, v89
	v_or_b32_e32 v88, 32, v142
	v_lshl_add_u64 v[44:45], v[146:147], 0, s[20:21]
	v_addc_co_u32_e32 v47, vcc, 0, v147, vcc
	v_cvt_pk_f16_f32 v28, v28, v29
	v_cvt_pk_f16_f32 v29, v30, v31
	v_cvt_pk_f16_f32 v30, v24, v25
	v_cvt_pk_f16_f32 v31, v26, v27
	v_cvt_pk_f16_f32 v111, v106, v107
	v_lshlrev_b64 v[104:105], 14, v[104:105]
	v_ashrrev_i32_e32 v89, 31, v88
	v_cvt_pk_f16_f32 v76, v76, v77
	v_cvt_pk_f16_f32 v77, v78, v79
	v_cvt_pk_f16_f32 v78, v72, v73
	v_or_b32_e32 v72, 48, v142
	global_store_dwordx4 v[44:45], v[28:31], off offset:256 sc1 nt
	global_store_dwordx4 v[146:147], v[108:111], off offset:256 sc1 nt
	v_cvt_pk_f16_f32 v95, v90, v91
	v_add_co_u32_e32 v30, vcc, s73, v146
	v_lshl_add_u64 v[108:109], v[144:145], 0, v[104:105]
	v_lshlrev_b64 v[88:89], 14, v[88:89]
	v_ashrrev_i32_e32 v73, 31, v72
	v_lshl_add_u64 v[28:29], v[146:147], 0, s[22:23]
	v_addc_co_u32_e32 v31, vcc, 0, v147, vcc
	v_cvt_pk_f16_f32 v12, v12, v13
	v_cvt_pk_f16_f32 v13, v14, v15
	v_cvt_pk_f16_f32 v14, v8, v9
	v_cvt_pk_f16_f32 v15, v10, v11
	global_store_dwordx4 v[108:109], v[92:95], off offset:256 sc1 nt
	v_cvt_pk_f16_f32 v79, v74, v75
	v_lshlrev_b64 v[72:73], 14, v[72:73]
	v_lshl_add_u64 v[92:93], v[144:145], 0, v[88:89]
	global_store_dwordx4 v[28:29], v[12:15], off offset:256 sc1 nt
	v_cvt_pk_f16_f32 v124, v124, v125
	v_cvt_pk_f16_f32 v125, v126, v127
	v_add_co_u32_e32 v14, vcc, 0x2c0000, v146
	v_cvt_pk_f16_f32 v126, v120, v121
	v_cvt_pk_f16_f32 v127, v122, v123
	v_cvt_pk_f16_f32 v104, v116, v117
	v_cvt_pk_f16_f32 v105, v118, v119
	v_cvt_pk_f16_f32 v106, v112, v113
	v_cvt_pk_f16_f32 v107, v114, v115
	v_cvt_pk_f16_f32 v88, v100, v101
	v_cvt_pk_f16_f32 v89, v102, v103
	v_cvt_pk_f16_f32 v90, v96, v97
	v_cvt_pk_f16_f32 v91, v98, v99
	global_store_dwordx4 v[92:93], v[76:79], off offset:256 sc1 nt
	v_cvt_pk_f16_f32 v74, v80, v81
	v_cvt_pk_f16_f32 v75, v82, v83
	v_lshl_add_u64 v[76:77], v[144:145], 0, v[72:73]
	v_cvt_pk_f16_f32 v72, v84, v85
	v_cvt_pk_f16_f32 v73, v86, v87
	v_cvt_pk_f16_f32 v71, v66, v67
	v_cvt_pk_f16_f32 v63, v58, v59
	v_cvt_pk_f16_f32 v40, v52, v53
	v_cvt_pk_f16_f32 v41, v54, v55
	v_cvt_pk_f16_f32 v42, v48, v49
	v_cvt_pk_f16_f32 v43, v50, v51
	v_cvt_pk_f16_f32 v24, v36, v37
	v_cvt_pk_f16_f32 v25, v38, v39
	v_cvt_pk_f16_f32 v26, v32, v33
	v_cvt_pk_f16_f32 v27, v34, v35
	v_lshl_add_u64 v[12:13], v[146:147], 0, s[24:25]
	v_cvt_pk_f16_f32 v8, v20, v21
	v_cvt_pk_f16_f32 v9, v22, v23
	v_cvt_pk_f16_f32 v10, v16, v17
	v_cvt_pk_f16_f32 v11, v18, v19
	v_addc_co_u32_e32 v15, vcc, 0, v147, vcc
	v_cvt_pk_f16_f32 v4, v4, v5
	v_cvt_pk_f16_f32 v5, v6, v7
	v_cvt_pk_f16_f32 v6, v0, v1
	v_cvt_pk_f16_f32 v7, v2, v3
	global_store_dwordx4 v[146:147], v[124:127], off sc1 nt
	global_store_dwordx4 v[108:109], v[104:107], off sc1 nt
	global_store_dwordx4 v[92:93], v[88:91], off sc1 nt
	global_store_dwordx4 v[76:77], v[72:75], off sc1 nt
	global_store_dwordx4 v[76:77], v[68:71], off offset:256 sc1 nt
	global_store_dwordx4 v[56:57], v[60:63], off sc1 nt
	global_store_dwordx4 v[46:47], v[40:43], off sc1 nt
	global_store_dwordx4 v[30:31], v[24:27], off sc1 nt
	global_store_dwordx4 v[14:15], v[8:11], off sc1 nt
	global_store_dwordx4 v[12:13], v[4:7], off offset:256 sc1 nt
	s_andn2_b64 vcc, exec, s[0:1]
	s_mov_b64 s[0:1], -1
	s_cbranch_vccnz .LBB0_93

;     __device__ __forceinline__ void operator()(const f32x4 (&acc)[2][2][4][2], const Unit& u, int wr, int wc, int fr, int fq) const {
;         const int row0 = u.pm * BM + wr * 64 + fr;
;         const int c0 = u.pn * 128 + 32 * wc + 8 * fq;
;         constexpr float DS = 1.f / (F8_SU * F8_SW);
;         f32x4 ba[2], bb[2];
; #pragma unroll
;         for (int n = 0; n < 2; ++n) { ba[n] = *(const f32x4*)(gbias + c0 + 4 * n); bb[n] = *(const f32x4*)(gbias + D + c0 + 4 * n); }
; #pragma unroll
;         for (int ai = 0; ai < 2; ++ai)
; #pragma unroll
;             for (int m = 0; m < 4; ++m) {
;                 h16* rowp = PG + (size_t)(u.pm * 32 + u.pn) * 65536 + (ai * 4 + m) * 4096 + (wr * 4 + wc) * 512 + (fq * 16 + fr) * 8;
;                 float r[8], sg[8];
; #pragma unroll
;                 for (int n = 0; n < 2; ++n)
; #pragma unroll
;                     for (int j = 0; j < 4; ++j) { const float ea = __expf(-(acc[ai][0][m][n][j] * DS + ba[n][j])), eb = __expf(-(acc[ai][1][m][n][j] * DS + bb[n][j]));
;                         const float pa = 1.f + ea, pb = 1.f + eb, rp = __builtin_amdgcn_rcpf(pa * pb);
;                         sg[4 * n + j] = pa * rp; r[4 * n + j] = pb * pb * rp; }
;                 u32x4 w; w.x = pkh(r[0], r[1]); w.y = pkh(r[2], r[3]); w.z = pkh(r[4], r[5]); w.w = pkh(r[6], r[7]);
;                 *(u32x4*)rowp = w;
;                 w.x = pkh(sg[0], sg[1]); w.y = pkh(sg[2], sg[3]); w.z = pkh(sg[4], sg[5]); w.w = pkh(sg[6], sg[7]);
;                 *(u32x4*)(rowp + 32768) = w; }
.LBB0_160:
	v_lshl_or_b32 v0, s27, 7, v183
	v_ashrrev_i32_e32 v1, 31, v0
	v_lshlrev_b64 v[0:1], 2, v[0:1]
	s_nop 15
	s_nop 15
	v_lshl_add_u64 v[2:3], s[8:9], 0, v[0:1]
	v_lshl_add_u64 v[0:1], s[14:15], 0, v[0:1]
	global_load_dwordx4 v[12:15], v[2:3], off
	global_load_dwordx4 v[8:11], v[0:1], off
	global_load_dwordx4 v[4:7], v[2:3], off offset:16
	s_nop 0
	global_load_dwordx4 v[0:3], v[0:1], off offset:16
	s_lshl_b32 s19, s26, 5
	s_add_i32 s26, s19, s27
	s_ashr_i32 s27, s26, 31
	s_lshl_b64 s[26:27], s[26:27], 17
	s_add_u32 s19, s53, s26
	s_addc_u32 s21, s7, s27
	s_add_u32 s26, s19, s16
	s_addc_u32 s27, s21, s17
	v_lshl_add_u64 v[16:17], s[26:27], 0, v[164:165]
	s_waitcnt vmcnt(0)
	v_fmamk_f32 v18, v156, 0x3a000000, v12
	v_fmamk_f32 v19, v148, 0x3a000000, v8
	v_fmamk_f32 v20, v157, 0x3a000000, v13
	v_fmamk_f32 v21, v149, 0x3a000000, v9
	v_fmamk_f32 v22, v158, 0x3a000000, v14
	v_fmamk_f32 v23, v150, 0x3a000000, v10
	v_fmamk_f32 v24, v159, 0x3a000000, v15
	v_fmamk_f32 v25, v151, 0x3a000000, v11
	v_fmamk_f32 v26, v152, 0x3a000000, v4
	v_fmamk_f32 v27, v144, 0x3a000000, v0
	v_fmamk_f32 v28, v153, 0x3a000000, v5
	v_fmamk_f32 v29, v145, 0x3a000000, v1
	v_fmamk_f32 v30, v154, 0x3a000000, v6
	v_fmamk_f32 v31, v146, 0x3a000000, v2
	v_fmamk_f32 v144, v155, 0x3a000000, v7
	v_fmamk_f32 v145, v147, 0x3a000000, v3
	v_mul_f32_e32 v18, 0xbfb8aa3b, v18
	v_mul_f32_e32 v19, 0xbfb8aa3b, v19
	v_mul_f32_e32 v146, 0xbfb8aa3b, v20
	v_mul_f32_e32 v21, 0xbfb8aa3b, v21
	v_mul_f32_e32 v22, 0xbfb8aa3b, v22
	v_mul_f32_e32 v23, 0xbfb8aa3b, v23
	v_mul_f32_e32 v147, 0xbfb8aa3b, v24
	v_mul_f32_e32 v25, 0xbfb8aa3b, v25
	v_mul_f32_e32 v26, 0xbfb8aa3b, v26
	v_mul_f32_e32 v27, 0xbfb8aa3b, v27
	v_mul_f32_e32 v148, 0xbfb8aa3b, v28
	v_mul_f32_e32 v29, 0xbfb8aa3b, v29
	v_mul_f32_e32 v30, 0xbfb8aa3b, v30
	v_mul_f32_e32 v31, 0xbfb8aa3b, v31
	v_mul_f32_e32 v149, 0xbfb8aa3b, v144
	v_mul_f32_e32 v145, 0xbfb8aa3b, v145
	v_exp_f32_e32 v18, v18
	v_exp_f32_e32 v20, v19
	v_exp_f32_e32 v19, v146
	v_exp_f32_e32 v21, v21
	v_exp_f32_e32 v22, v22
	v_exp_f32_e32 v24, v23
	v_exp_f32_e32 v23, v147
	v_exp_f32_e32 v25, v25
	v_exp_f32_e32 v26, v26
	v_exp_f32_e32 v28, v27
	v_exp_f32_e32 v27, v148
	v_exp_f32_e32 v29, v29
	v_exp_f32_e32 v30, v30
	v_exp_f32_e32 v144, v31
	v_exp_f32_e32 v31, v149
	v_exp_f32_e32 v145, v145
	v_pk_add_f32 v[20:21], v[20:21], 1.0 op_sel_hi:[1,0]
	v_pk_add_f32 v[24:25], v[24:25], 1.0 op_sel_hi:[1,0]
	v_pk_add_f32 v[18:19], v[18:19], 1.0 op_sel_hi:[1,0]
	v_pk_add_f32 v[22:23], v[22:23], 1.0 op_sel_hi:[1,0]
	v_pk_add_f32 v[28:29], v[28:29], 1.0 op_sel_hi:[1,0]
	v_pk_add_f32 v[144:145], v[144:145], 1.0 op_sel_hi:[1,0]
	v_pk_add_f32 v[26:27], v[26:27], 1.0 op_sel_hi:[1,0]
	v_pk_add_f32 v[30:31], v[30:31], 1.0 op_sel_hi:[1,0]
	v_pk_mul_f32 v[146:147], v[20:21], v[20:21]
	v_pk_mul_f32 v[148:149], v[24:25], v[24:25]
	v_pk_mul_f32 v[20:21], v[18:19], v[20:21]
	v_pk_mul_f32 v[24:25], v[22:23], v[24:25]
	v_pk_mul_f32 v[150:151], v[28:29], v[28:29]
	v_pk_mul_f32 v[152:153], v[144:145], v[144:145]
	v_pk_mul_f32 v[28:29], v[26:27], v[28:29]
	v_pk_mul_f32 v[144:145], v[30:31], v[144:145]
	v_rcp_f32_e32 v20, v20
	v_rcp_f32_e32 v21, v21
	v_rcp_f32_e32 v24, v24
	v_rcp_f32_e32 v25, v25
	v_rcp_f32_e32 v28, v28
	v_rcp_f32_e32 v29, v29
	v_rcp_f32_e32 v144, v144
	v_rcp_f32_e32 v145, v145
	v_pk_mul_f32 v[154:155], v[18:19], v[20:21]
	v_pk_mul_f32 v[18:19], v[146:147], v[20:21]
	v_pk_mul_f32 v[20:21], v[22:23], v[24:25]
	v_pk_mul_f32 v[24:25], v[148:149], v[24:25]
	v_pk_mul_f32 v[26:27], v[26:27], v[28:29]
	v_cvt_pk_f16_f32 v23, v20, v21
	v_pk_mul_f32 v[20:21], v[150:151], v[28:29]
	v_pk_mul_f32 v[28:29], v[152:153], v[144:145]
	v_cvt_pk_f16_f32 v18, v18, v19
	v_cvt_pk_f16_f32 v19, v24, v25
	v_cvt_pk_f16_f32 v20, v20, v21
	v_cvt_pk_f16_f32 v21, v28, v29
	v_cvt_pk_f16_f32 v24, v26, v27
	v_pk_mul_f32 v[26:27], v[30:31], v[144:145]
	global_store_dwordx4 v164, v[18:21], s[26:27] sc1 nt
	v_cvt_pk_f16_f32 v22, v154, v155
	v_cvt_pk_f16_f32 v25, v26, v27
	v_add_co_u32_e32 v18, vcc, s59, v16
	v_fmamk_f32 v21, v133, 0x3a000000, v9
	s_nop 0
	v_addc_co_u32_e32 v19, vcc, 0, v17, vcc
	global_store_dwordx4 v[18:19], v[22:25], off sc1 nt
	v_fmamk_f32 v19, v132, 0x3a000000, v8
	v_mul_f32_e32 v19, 0xbfb8aa3b, v19
	v_fmamk_f32 v18, v140, 0x3a000000, v12
	v_exp_f32_e32 v20, v19
	v_fmamk_f32 v19, v141, 0x3a000000, v13
	v_mul_f32_e32 v18, 0xbfb8aa3b, v18
	v_mul_f32_e32 v19, 0xbfb8aa3b, v19
	v_mul_f32_e32 v21, 0xbfb8aa3b, v21
	v_exp_f32_e32 v18, v18
	v_exp_f32_e32 v19, v19
	v_exp_f32_e32 v21, v21
	v_fmamk_f32 v23, v134, 0x3a000000, v10
	v_mul_f32_e32 v23, 0xbfb8aa3b, v23
	v_fmamk_f32 v27, v128, 0x3a000000, v0
	v_fmamk_f32 v22, v142, 0x3a000000, v14
	v_exp_f32_e32 v24, v23
	v_fmamk_f32 v23, v143, 0x3a000000, v15
	v_fmamk_f32 v25, v135, 0x3a000000, v11
	v_mul_f32_e32 v27, 0xbfb8aa3b, v27
	v_mul_f32_e32 v22, 0xbfb8aa3b, v22
	v_mul_f32_e32 v23, 0xbfb8aa3b, v23
	v_mul_f32_e32 v25, 0xbfb8aa3b, v25
	v_fmamk_f32 v26, v136, 0x3a000000, v4
	v_exp_f32_e32 v28, v27
	v_fmamk_f32 v27, v137, 0x3a000000, v5
	v_fmamk_f32 v29, v129, 0x3a000000, v1
	v_pk_add_f32 v[20:21], v[20:21], 1.0 op_sel_hi:[1,0]
	v_pk_add_f32 v[18:19], v[18:19], 1.0 op_sel_hi:[1,0]
	v_exp_f32_e32 v22, v22
	v_exp_f32_e32 v23, v23
	v_exp_f32_e32 v25, v25
	v_mul_f32_e32 v26, 0xbfb8aa3b, v26
	v_mul_f32_e32 v27, 0xbfb8aa3b, v27
	v_mul_f32_e32 v29, 0xbfb8aa3b, v29
	v_fmamk_f32 v31, v130, 0x3a000000, v2
	v_fmamk_f32 v129, v131, 0x3a000000, v3
	v_pk_mul_f32 v[130:131], v[20:21], v[20:21]
	v_pk_mul_f32 v[20:21], v[18:19], v[20:21]
	v_exp_f32_e32 v26, v26
	v_exp_f32_e32 v27, v27
	v_exp_f32_e32 v29, v29
	v_rcp_f32_e32 v20, v20
	v_rcp_f32_e32 v21, v21
	v_mul_f32_e32 v31, 0xbfb8aa3b, v31
;     __device__ __forceinline__ void operator()(const f32x4 (&acc)[2][2][4][2], const Unit& u, int wr, int wc, int fr, int fq) const {
;     ...
;         for (int ai = 0; ai < 2; ++ai)
; #pragma unroll
;             for (int m = 0; m < 4; ++m) {
;                 h16* rowp = PG + (size_t)(u.pm * 32 + u.pn) * 65536 + (ai * 4 + m) * 4096 + (wr * 4 + wc) * 512 + (fq * 16 + fr) * 8;
;                 float r[8], sg[8];
; #pragma unroll
;                 for (int n = 0; n < 2; ++n)
; #pragma unroll
;                     for (int j = 0; j < 4; ++j) { const float ea = __expf(-(acc[ai][0][m][n][j] * DS + ba[n][j])), eb = __expf(-(acc[ai][1][m][n][j] * DS + bb[n][j]));
;                         const float pa = 1.f + ea, pb = 1.f + eb, rp = __builtin_amdgcn_rcpf(pa * pb);
;                         sg[4 * n + j] = pa * rp; r[4 * n + j] = pb * pb * rp; }
;                 u32x4 w; w.x = pkh(r[0], r[1]); w.y = pkh(r[2], r[3]); w.z = pkh(r[4], r[5]); w.w = pkh(r[6], r[7]);
;                 *(u32x4*)rowp = w;
;                 w.x = pkh(sg[0], sg[1]); w.y = pkh(sg[2], sg[3]); w.z = pkh(sg[4], sg[5]); w.w = pkh(sg[6], sg[7]);
;                 *(u32x4*)(rowp + 32768) = w; }
	v_pk_add_f32 v[24:25], v[24:25], 1.0 op_sel_hi:[1,0]
	v_pk_add_f32 v[140:141], v[22:23], 1.0 op_sel_hi:[1,0]
	v_fmamk_f32 v30, v138, 0x3a000000, v6
	v_exp_f32_e32 v128, v31
	v_fmamk_f32 v31, v139, 0x3a000000, v7
	v_pk_add_f32 v[28:29], v[28:29], 1.0 op_sel_hi:[1,0]
	v_pk_mul_f32 v[138:139], v[18:19], v[20:21]
	v_pk_mul_f32 v[18:19], v[140:141], v[24:25]
	v_pk_add_f32 v[26:27], v[26:27], 1.0 op_sel_hi:[1,0]
	v_mul_f32_e32 v30, 0xbfb8aa3b, v30
	v_mul_f32_e32 v31, 0xbfb8aa3b, v31
	v_mul_f32_e32 v129, 0xbfb8aa3b, v129
	v_pk_mul_f32 v[132:133], v[24:25], v[24:25]
	v_pk_mul_f32 v[134:135], v[28:29], v[28:29]
	v_rcp_f32_e32 v24, v18
	v_rcp_f32_e32 v25, v19
	v_pk_mul_f32 v[28:29], v[26:27], v[28:29]
	v_exp_f32_e32 v30, v30
	v_exp_f32_e32 v31, v31
	v_exp_f32_e32 v129, v129
	v_rcp_f32_e32 v28, v28
	v_rcp_f32_e32 v29, v29
	v_pk_mul_f32 v[18:19], v[130:131], v[20:21]
	v_pk_mul_f32 v[20:21], v[140:141], v[24:25]
	v_pk_mul_f32 v[24:25], v[132:133], v[24:25]
	v_pk_add_f32 v[128:129], v[128:129], 1.0 op_sel_hi:[1,0]
	v_cvt_pk_f16_f32 v18, v18, v19
	v_cvt_pk_f16_f32 v19, v24, v25
	v_pk_mul_f32 v[24:25], v[26:27], v[28:29]
	v_pk_add_f32 v[26:27], v[30:31], 1.0 op_sel_hi:[1,0]
	v_cvt_pk_f16_f32 v23, v20, v21
	v_pk_mul_f32 v[20:21], v[26:27], v[128:129]
	v_pk_mul_f32 v[136:137], v[128:129], v[128:129]
	v_rcp_f32_e32 v30, v20
	v_rcp_f32_e32 v31, v21
	v_pk_mul_f32 v[20:21], v[134:135], v[28:29]
	v_cvt_pk_f16_f32 v22, v138, v139
	v_cvt_pk_f16_f32 v20, v20, v21
	v_pk_mul_f32 v[28:29], v[136:137], v[30:31]
	v_pk_mul_f32 v[26:27], v[26:27], v[30:31]
	v_cvt_pk_f16_f32 v21, v28, v29
	v_add_co_u32_e32 v28, vcc, s57, v16
	v_cvt_pk_f16_f32 v24, v24, v25
	s_nop 0
	v_addc_co_u32_e32 v29, vcc, 0, v17, vcc
	global_store_dwordx4 v[28:29], v[18:21], off sc1 nt
	v_cvt_pk_f16_f32 v25, v26, v27
	v_fmamk_f32 v27, v112, 0x3a000000, v0
	v_add_co_u32_e32 v18, vcc, s60, v16
	v_fmamk_f32 v21, v117, 0x3a000000, v9
	s_nop 0
	v_addc_co_u32_e32 v19, vcc, 0, v17, vcc
	global_store_dwordx4 v[18:19], v[22:25], off sc1 nt
	v_fmamk_f32 v19, v116, 0x3a000000, v8
	v_mul_f32_e32 v19, 0xbfb8aa3b, v19
	v_fmamk_f32 v18, v124, 0x3a000000, v12
	v_exp_f32_e32 v20, v19
	v_fmamk_f32 v19, v125, 0x3a000000, v13
	v_mul_f32_e32 v18, 0xbfb8aa3b, v18
	v_mul_f32_e32 v19, 0xbfb8aa3b, v19
	v_mul_f32_e32 v21, 0xbfb8aa3b, v21
	v_exp_f32_e32 v18, v18
	v_exp_f32_e32 v19, v19
	v_exp_f32_e32 v21, v21
	v_fmamk_f32 v23, v118, 0x3a000000, v10
	v_mul_f32_e32 v23, 0xbfb8aa3b, v23
	v_fmamk_f32 v22, v126, 0x3a000000, v14
	v_exp_f32_e32 v24, v23
	v_fmamk_f32 v23, v127, 0x3a000000, v15
	v_fmamk_f32 v25, v119, 0x3a000000, v11
	v_mul_f32_e32 v27, 0xbfb8aa3b, v27
	v_mul_f32_e32 v22, 0xbfb8aa3b, v22
	v_mul_f32_e32 v23, 0xbfb8aa3b, v23
	v_mul_f32_e32 v25, 0xbfb8aa3b, v25
	v_fmamk_f32 v26, v120, 0x3a000000, v4
	v_exp_f32_e32 v28, v27
	v_fmamk_f32 v27, v121, 0x3a000000, v5
	v_fmamk_f32 v29, v113, 0x3a000000, v1
	v_pk_add_f32 v[20:21], v[20:21], 1.0 op_sel_hi:[1,0]
	v_pk_add_f32 v[18:19], v[18:19], 1.0 op_sel_hi:[1,0]
	v_exp_f32_e32 v22, v22
	v_exp_f32_e32 v23, v23
	v_exp_f32_e32 v25, v25
	v_mul_f32_e32 v26, 0xbfb8aa3b, v26
	v_mul_f32_e32 v27, 0xbfb8aa3b, v27
	v_mul_f32_e32 v29, 0xbfb8aa3b, v29
	v_fmamk_f32 v31, v114, 0x3a000000, v2
	v_fmamk_f32 v113, v115, 0x3a000000, v3
	v_pk_mul_f32 v[114:115], v[20:21], v[20:21]
	v_pk_mul_f32 v[20:21], v[18:19], v[20:21]
	v_exp_f32_e32 v26, v26
	v_exp_f32_e32 v27, v27
	v_exp_f32_e32 v29, v29
	v_rcp_f32_e32 v20, v20
	v_rcp_f32_e32 v21, v21
	v_mul_f32_e32 v31, 0xbfb8aa3b, v31
	v_pk_add_f32 v[24:25], v[24:25], 1.0 op_sel_hi:[1,0]
	v_pk_add_f32 v[124:125], v[22:23], 1.0 op_sel_hi:[1,0]
	v_fmamk_f32 v30, v122, 0x3a000000, v6
	v_exp_f32_e32 v112, v31
	v_fmamk_f32 v31, v123, 0x3a000000, v7
	v_pk_add_f32 v[28:29], v[28:29], 1.0 op_sel_hi:[1,0]
	v_pk_mul_f32 v[122:123], v[18:19], v[20:21]
	v_pk_mul_f32 v[18:19], v[124:125], v[24:25]
	v_pk_add_f32 v[26:27], v[26:27], 1.0 op_sel_hi:[1,0]
	v_mul_f32_e32 v30, 0xbfb8aa3b, v30
	v_mul_f32_e32 v31, 0xbfb8aa3b, v31
	v_mul_f32_e32 v113, 0xbfb8aa3b, v113
	v_pk_mul_f32 v[116:117], v[24:25], v[24:25]
	v_pk_mul_f32 v[118:119], v[28:29], v[28:29]
	v_rcp_f32_e32 v24, v18
	v_rcp_f32_e32 v25, v19
	v_pk_mul_f32 v[28:29], v[26:27], v[28:29]
	v_exp_f32_e32 v30, v30
	v_exp_f32_e32 v31, v31
	v_exp_f32_e32 v113, v113
	v_rcp_f32_e32 v28, v28
	v_rcp_f32_e32 v29, v29
	v_pk_mul_f32 v[18:19], v[114:115], v[20:21]
	v_pk_mul_f32 v[20:21], v[124:125], v[24:25]
	v_pk_mul_f32 v[24:25], v[116:117], v[24:25]
	v_pk_add_f32 v[112:113], v[112:113], 1.0 op_sel_hi:[1,0]
	v_cvt_pk_f16_f32 v18, v18, v19
	v_cvt_pk_f16_f32 v19, v24, v25
	v_pk_mul_f32 v[24:25], v[26:27], v[28:29]
	v_pk_add_f32 v[26:27], v[30:31], 1.0 op_sel_hi:[1,0]
	v_cvt_pk_f16_f32 v23, v20, v21
	v_pk_mul_f32 v[20:21], v[26:27], v[112:113]
	v_pk_mul_f32 v[120:121], v[112:113], v[112:113]
	v_rcp_f32_e32 v30, v20
	v_rcp_f32_e32 v31, v21
	v_pk_mul_f32 v[20:21], v[118:119], v[28:29]
	v_cvt_pk_f16_f32 v22, v122, v123
	v_cvt_pk_f16_f32 v20, v20, v21
	v_pk_mul_f32 v[28:29], v[120:121], v[30:31]
	v_pk_mul_f32 v[26:27], v[26:27], v[30:31]
	v_cvt_pk_f16_f32 v21, v28, v29
	v_add_co_u32_e32 v28, vcc, s63, v16
	v_cvt_pk_f16_f32 v24, v24, v25
	s_nop 0
	v_addc_co_u32_e32 v29, vcc, 0, v17, vcc
	global_store_dwordx4 v[28:29], v[18:21], off sc1 nt
	v_cvt_pk_f16_f32 v25, v26, v27
	v_fmamk_f32 v27, v96, 0x3a000000, v0
	v_add_co_u32_e32 v18, vcc, s61, v16
	v_fmamk_f32 v21, v101, 0x3a000000, v9
	s_nop 0
	v_addc_co_u32_e32 v19, vcc, 0, v17, vcc
	global_store_dwordx4 v[18:19], v[22:25], off sc1 nt
	v_fmamk_f32 v19, v100, 0x3a000000, v8
	v_mul_f32_e32 v19, 0xbfb8aa3b, v19
	v_fmamk_f32 v18, v108, 0x3a000000, v12
	v_exp_f32_e32 v20, v19
;     __device__ __forceinline__ void operator()(const f32x4 (&acc)[2][2][4][2], const Unit& u, int wr, int wc, int fr, int fq) const {
;     ...
;         for (int ai = 0; ai < 2; ++ai)
; #pragma unroll
;             for (int m = 0; m < 4; ++m) {
;                 h16* rowp = PG + (size_t)(u.pm * 32 + u.pn) * 65536 + (ai * 4 + m) * 4096 + (wr * 4 + wc) * 512 + (fq * 16 + fr) * 8;
;                 float r[8], sg[8];
; #pragma unroll
;                 for (int n = 0; n < 2; ++n)
; #pragma unroll
;                     for (int j = 0; j < 4; ++j) { const float ea = __expf(-(acc[ai][0][m][n][j] * DS + ba[n][j])), eb = __expf(-(acc[ai][1][m][n][j] * DS + bb[n][j]));
;                         const float pa = 1.f + ea, pb = 1.f + eb, rp = __builtin_amdgcn_rcpf(pa * pb);
;                         sg[4 * n + j] = pa * rp; r[4 * n + j] = pb * pb * rp; }
;                 u32x4 w; w.x = pkh(r[0], r[1]); w.y = pkh(r[2], r[3]); w.z = pkh(r[4], r[5]); w.w = pkh(r[6], r[7]);
;                 *(u32x4*)rowp = w;
;                 w.x = pkh(sg[0], sg[1]); w.y = pkh(sg[2], sg[3]); w.z = pkh(sg[4], sg[5]); w.w = pkh(sg[6], sg[7]);
;                 *(u32x4*)(rowp + 32768) = w; }
	v_fmamk_f32 v19, v109, 0x3a000000, v13
	v_mul_f32_e32 v18, 0xbfb8aa3b, v18
	v_mul_f32_e32 v19, 0xbfb8aa3b, v19
	v_mul_f32_e32 v21, 0xbfb8aa3b, v21
	v_exp_f32_e32 v18, v18
	v_exp_f32_e32 v19, v19
	v_exp_f32_e32 v21, v21
	v_fmamk_f32 v23, v102, 0x3a000000, v10
	v_mul_f32_e32 v23, 0xbfb8aa3b, v23
	v_fmamk_f32 v22, v110, 0x3a000000, v14
	v_exp_f32_e32 v24, v23
	v_fmamk_f32 v23, v111, 0x3a000000, v15
	v_fmamk_f32 v25, v103, 0x3a000000, v11
	v_mul_f32_e32 v27, 0xbfb8aa3b, v27
	v_mul_f32_e32 v22, 0xbfb8aa3b, v22
	v_mul_f32_e32 v23, 0xbfb8aa3b, v23
	v_mul_f32_e32 v25, 0xbfb8aa3b, v25
	v_fmamk_f32 v26, v104, 0x3a000000, v4
	v_exp_f32_e32 v28, v27
	v_fmamk_f32 v27, v105, 0x3a000000, v5
	v_fmamk_f32 v29, v97, 0x3a000000, v1
	v_pk_add_f32 v[20:21], v[20:21], 1.0 op_sel_hi:[1,0]
	v_pk_add_f32 v[18:19], v[18:19], 1.0 op_sel_hi:[1,0]
	v_exp_f32_e32 v22, v22
	v_exp_f32_e32 v23, v23
	v_exp_f32_e32 v25, v25
	v_mul_f32_e32 v26, 0xbfb8aa3b, v26
	v_mul_f32_e32 v27, 0xbfb8aa3b, v27
	v_mul_f32_e32 v29, 0xbfb8aa3b, v29
	v_fmamk_f32 v31, v98, 0x3a000000, v2
	v_fmamk_f32 v97, v99, 0x3a000000, v3
	v_pk_mul_f32 v[98:99], v[20:21], v[20:21]
	v_pk_mul_f32 v[20:21], v[18:19], v[20:21]
	v_exp_f32_e32 v26, v26
	v_exp_f32_e32 v27, v27
	v_exp_f32_e32 v29, v29
	v_rcp_f32_e32 v20, v20
	v_rcp_f32_e32 v21, v21
	v_mul_f32_e32 v31, 0xbfb8aa3b, v31
	v_pk_add_f32 v[24:25], v[24:25], 1.0 op_sel_hi:[1,0]
	v_pk_add_f32 v[108:109], v[22:23], 1.0 op_sel_hi:[1,0]
	v_fmamk_f32 v30, v106, 0x3a000000, v6
	v_exp_f32_e32 v96, v31
	v_fmamk_f32 v31, v107, 0x3a000000, v7
	v_pk_add_f32 v[28:29], v[28:29], 1.0 op_sel_hi:[1,0]
	v_pk_mul_f32 v[106:107], v[18:19], v[20:21]
	v_pk_mul_f32 v[18:19], v[108:109], v[24:25]
	v_pk_add_f32 v[26:27], v[26:27], 1.0 op_sel_hi:[1,0]
	v_mul_f32_e32 v30, 0xbfb8aa3b, v30
	v_mul_f32_e32 v31, 0xbfb8aa3b, v31
	v_mul_f32_e32 v97, 0xbfb8aa3b, v97
	v_pk_mul_f32 v[100:101], v[24:25], v[24:25]
	v_pk_mul_f32 v[102:103], v[28:29], v[28:29]
	v_rcp_f32_e32 v24, v18
	v_rcp_f32_e32 v25, v19
	v_pk_mul_f32 v[28:29], v[26:27], v[28:29]
	v_exp_f32_e32 v30, v30
	v_exp_f32_e32 v31, v31
	v_exp_f32_e32 v97, v97
	v_rcp_f32_e32 v28, v28
	v_rcp_f32_e32 v29, v29
	v_pk_mul_f32 v[18:19], v[98:99], v[20:21]
	v_pk_mul_f32 v[20:21], v[108:109], v[24:25]
	v_pk_mul_f32 v[24:25], v[100:101], v[24:25]
	v_pk_add_f32 v[96:97], v[96:97], 1.0 op_sel_hi:[1,0]
	v_cvt_pk_f16_f32 v18, v18, v19
	v_cvt_pk_f16_f32 v19, v24, v25
	v_pk_mul_f32 v[24:25], v[26:27], v[28:29]
	v_pk_add_f32 v[26:27], v[30:31], 1.0 op_sel_hi:[1,0]
	v_cvt_pk_f16_f32 v23, v20, v21
	v_pk_mul_f32 v[20:21], v[26:27], v[96:97]
	v_pk_mul_f32 v[104:105], v[96:97], v[96:97]
	v_rcp_f32_e32 v30, v20
	v_rcp_f32_e32 v31, v21
	v_pk_mul_f32 v[20:21], v[102:103], v[28:29]
	v_cvt_pk_f16_f32 v22, v106, v107
	v_cvt_pk_f16_f32 v20, v20, v21
	v_pk_mul_f32 v[28:29], v[104:105], v[30:31]
	v_pk_mul_f32 v[26:27], v[26:27], v[30:31]
	v_cvt_pk_f16_f32 v21, v28, v29
	v_add_co_u32_e32 v28, vcc, s66, v16
	v_cvt_pk_f16_f32 v24, v24, v25
	s_nop 0
	v_addc_co_u32_e32 v29, vcc, 0, v17, vcc
	global_store_dwordx4 v[28:29], v[18:21], off sc1 nt
	v_cvt_pk_f16_f32 v25, v26, v27
	v_fmamk_f32 v27, v80, 0x3a000000, v0
	v_add_co_u32_e32 v18, vcc, s62, v16
	v_fmamk_f32 v21, v85, 0x3a000000, v9
	s_nop 0
	v_addc_co_u32_e32 v19, vcc, 0, v17, vcc
	global_store_dwordx4 v[18:19], v[22:25], off sc1 nt
	v_fmamk_f32 v19, v84, 0x3a000000, v8
	v_mul_f32_e32 v19, 0xbfb8aa3b, v19
	v_fmamk_f32 v18, v92, 0x3a000000, v12
	v_exp_f32_e32 v20, v19
	v_fmamk_f32 v19, v93, 0x3a000000, v13
	v_mul_f32_e32 v18, 0xbfb8aa3b, v18
	v_mul_f32_e32 v19, 0xbfb8aa3b, v19
	v_mul_f32_e32 v21, 0xbfb8aa3b, v21
	v_exp_f32_e32 v18, v18
	v_exp_f32_e32 v19, v19
	v_exp_f32_e32 v21, v21
	v_fmamk_f32 v23, v86, 0x3a000000, v10
	v_mul_f32_e32 v23, 0xbfb8aa3b, v23
	v_fmamk_f32 v22, v94, 0x3a000000, v14
	v_exp_f32_e32 v24, v23
	v_fmamk_f32 v23, v95, 0x3a000000, v15
	v_fmamk_f32 v25, v87, 0x3a000000, v11
	v_mul_f32_e32 v27, 0xbfb8aa3b, v27
	v_mul_f32_e32 v22, 0xbfb8aa3b, v22
	v_mul_f32_e32 v23, 0xbfb8aa3b, v23
	v_mul_f32_e32 v25, 0xbfb8aa3b, v25
	v_fmamk_f32 v26, v88, 0x3a000000, v4
	v_exp_f32_e32 v28, v27
	v_fmamk_f32 v27, v89, 0x3a000000, v5
	v_fmamk_f32 v29, v81, 0x3a000000, v1
	v_pk_add_f32 v[20:21], v[20:21], 1.0 op_sel_hi:[1,0]
	v_pk_add_f32 v[18:19], v[18:19], 1.0 op_sel_hi:[1,0]
	v_exp_f32_e32 v22, v22
	v_exp_f32_e32 v23, v23
	v_exp_f32_e32 v25, v25
	v_mul_f32_e32 v26, 0xbfb8aa3b, v26
	v_mul_f32_e32 v27, 0xbfb8aa3b, v27
	v_mul_f32_e32 v29, 0xbfb8aa3b, v29
	v_fmamk_f32 v31, v82, 0x3a000000, v2
	v_fmamk_f32 v81, v83, 0x3a000000, v3
	v_pk_mul_f32 v[82:83], v[20:21], v[20:21]
	v_pk_mul_f32 v[20:21], v[18:19], v[20:21]
	v_exp_f32_e32 v26, v26
	v_exp_f32_e32 v27, v27
	v_exp_f32_e32 v29, v29
	v_rcp_f32_e32 v20, v20
	v_rcp_f32_e32 v21, v21
	v_mul_f32_e32 v31, 0xbfb8aa3b, v31
	v_pk_add_f32 v[24:25], v[24:25], 1.0 op_sel_hi:[1,0]
	v_pk_add_f32 v[92:93], v[22:23], 1.0 op_sel_hi:[1,0]
	v_fmamk_f32 v30, v90, 0x3a000000, v6
	v_exp_f32_e32 v80, v31
	v_fmamk_f32 v31, v91, 0x3a000000, v7
	v_pk_add_f32 v[28:29], v[28:29], 1.0 op_sel_hi:[1,0]
	v_pk_mul_f32 v[90:91], v[18:19], v[20:21]
	v_pk_mul_f32 v[18:19], v[92:93], v[24:25]
	v_pk_add_f32 v[26:27], v[26:27], 1.0 op_sel_hi:[1,0]
	v_mul_f32_e32 v30, 0xbfb8aa3b, v30
	v_mul_f32_e32 v31, 0xbfb8aa3b, v31
	v_mul_f32_e32 v81, 0xbfb8aa3b, v81
	v_pk_mul_f32 v[84:85], v[24:25], v[24:25]
	v_pk_mul_f32 v[86:87], v[28:29], v[28:29]
	v_rcp_f32_e32 v24, v18
	v_rcp_f32_e32 v25, v19
	v_pk_mul_f32 v[28:29], v[26:27], v[28:29]
	v_exp_f32_e32 v30, v30
	v_exp_f32_e32 v31, v31
	v_exp_f32_e32 v81, v81
	v_rcp_f32_e32 v28, v28
	v_rcp_f32_e32 v29, v29
	v_pk_mul_f32 v[18:19], v[82:83], v[20:21]
;     __device__ __forceinline__ void operator()(const f32x4 (&acc)[2][2][4][2], const Unit& u, int wr, int wc, int fr, int fq) const {
;     ...
;         for (int ai = 0; ai < 2; ++ai)
; #pragma unroll
;             for (int m = 0; m < 4; ++m) {
;                 h16* rowp = PG + (size_t)(u.pm * 32 + u.pn) * 65536 + (ai * 4 + m) * 4096 + (wr * 4 + wc) * 512 + (fq * 16 + fr) * 8;
;                 float r[8], sg[8];
; #pragma unroll
;                 for (int n = 0; n < 2; ++n)
; #pragma unroll
;                     for (int j = 0; j < 4; ++j) { const float ea = __expf(-(acc[ai][0][m][n][j] * DS + ba[n][j])), eb = __expf(-(acc[ai][1][m][n][j] * DS + bb[n][j]));
;                         const float pa = 1.f + ea, pb = 1.f + eb, rp = __builtin_amdgcn_rcpf(pa * pb);
;                         sg[4 * n + j] = pa * rp; r[4 * n + j] = pb * pb * rp; }
;                 u32x4 w; w.x = pkh(r[0], r[1]); w.y = pkh(r[2], r[3]); w.z = pkh(r[4], r[5]); w.w = pkh(r[6], r[7]);
;                 *(u32x4*)rowp = w;
;                 w.x = pkh(sg[0], sg[1]); w.y = pkh(sg[2], sg[3]); w.z = pkh(sg[4], sg[5]); w.w = pkh(sg[6], sg[7]);
;                 *(u32x4*)(rowp + 32768) = w; }
	v_pk_mul_f32 v[20:21], v[92:93], v[24:25]
	v_pk_mul_f32 v[24:25], v[84:85], v[24:25]
	v_pk_add_f32 v[80:81], v[80:81], 1.0 op_sel_hi:[1,0]
	v_cvt_pk_f16_f32 v18, v18, v19
	v_cvt_pk_f16_f32 v19, v24, v25
	v_pk_mul_f32 v[24:25], v[26:27], v[28:29]
	v_pk_add_f32 v[26:27], v[30:31], 1.0 op_sel_hi:[1,0]
	v_cvt_pk_f16_f32 v23, v20, v21
	v_pk_mul_f32 v[20:21], v[26:27], v[80:81]
	v_pk_mul_f32 v[88:89], v[80:81], v[80:81]
	v_rcp_f32_e32 v30, v20
	v_rcp_f32_e32 v31, v21
	v_pk_mul_f32 v[20:21], v[86:87], v[28:29]
	v_cvt_pk_f16_f32 v22, v90, v91
	v_cvt_pk_f16_f32 v20, v20, v21
	v_pk_mul_f32 v[28:29], v[88:89], v[30:31]
	v_pk_mul_f32 v[26:27], v[26:27], v[30:31]
	v_cvt_pk_f16_f32 v21, v28, v29
	v_add_co_u32_e32 v28, vcc, s71, v16
	v_cvt_pk_f16_f32 v24, v24, v25
	s_nop 0
	v_addc_co_u32_e32 v29, vcc, 0, v17, vcc
	global_store_dwordx4 v[28:29], v[18:21], off sc1 nt
	v_cvt_pk_f16_f32 v25, v26, v27
	v_fmamk_f32 v27, v64, 0x3a000000, v0
	v_add_co_u32_e32 v18, vcc, s69, v16
	v_fmamk_f32 v21, v69, 0x3a000000, v9
	s_nop 0
	v_addc_co_u32_e32 v19, vcc, 0, v17, vcc
	global_store_dwordx4 v[18:19], v[22:25], off sc1 nt
	v_fmamk_f32 v19, v68, 0x3a000000, v8
	v_mul_f32_e32 v19, 0xbfb8aa3b, v19
	v_fmamk_f32 v18, v76, 0x3a000000, v12
	v_exp_f32_e32 v20, v19
	v_fmamk_f32 v19, v77, 0x3a000000, v13
	v_mul_f32_e32 v18, 0xbfb8aa3b, v18
	v_mul_f32_e32 v19, 0xbfb8aa3b, v19
	v_mul_f32_e32 v21, 0xbfb8aa3b, v21
	v_exp_f32_e32 v18, v18
	v_exp_f32_e32 v19, v19
	v_exp_f32_e32 v21, v21
	v_fmamk_f32 v23, v70, 0x3a000000, v10
	v_mul_f32_e32 v23, 0xbfb8aa3b, v23
	v_fmamk_f32 v22, v78, 0x3a000000, v14
	v_exp_f32_e32 v24, v23
	v_fmamk_f32 v23, v79, 0x3a000000, v15
	v_fmamk_f32 v25, v71, 0x3a000000, v11
	v_mul_f32_e32 v27, 0xbfb8aa3b, v27
	v_mul_f32_e32 v22, 0xbfb8aa3b, v22
	v_mul_f32_e32 v23, 0xbfb8aa3b, v23
	v_mul_f32_e32 v25, 0xbfb8aa3b, v25
	v_fmamk_f32 v26, v72, 0x3a000000, v4
	v_exp_f32_e32 v28, v27
	v_fmamk_f32 v27, v73, 0x3a000000, v5
	v_fmamk_f32 v29, v65, 0x3a000000, v1
	v_pk_add_f32 v[20:21], v[20:21], 1.0 op_sel_hi:[1,0]
	v_pk_add_f32 v[18:19], v[18:19], 1.0 op_sel_hi:[1,0]
	v_exp_f32_e32 v22, v22
	v_exp_f32_e32 v23, v23
	v_exp_f32_e32 v25, v25
	v_mul_f32_e32 v26, 0xbfb8aa3b, v26
	v_mul_f32_e32 v27, 0xbfb8aa3b, v27
	v_mul_f32_e32 v29, 0xbfb8aa3b, v29
	v_fmamk_f32 v31, v66, 0x3a000000, v2
	v_fmamk_f32 v65, v67, 0x3a000000, v3
	v_pk_mul_f32 v[66:67], v[20:21], v[20:21]
	v_pk_mul_f32 v[20:21], v[18:19], v[20:21]
	v_exp_f32_e32 v26, v26
	v_exp_f32_e32 v27, v27
	v_exp_f32_e32 v29, v29
	v_rcp_f32_e32 v20, v20
	v_rcp_f32_e32 v21, v21
	v_mul_f32_e32 v31, 0xbfb8aa3b, v31
	v_pk_add_f32 v[24:25], v[24:25], 1.0 op_sel_hi:[1,0]
	v_pk_add_f32 v[76:77], v[22:23], 1.0 op_sel_hi:[1,0]
	v_fmamk_f32 v30, v74, 0x3a000000, v6
	v_exp_f32_e32 v64, v31
	v_fmamk_f32 v31, v75, 0x3a000000, v7
	v_pk_add_f32 v[28:29], v[28:29], 1.0 op_sel_hi:[1,0]
	v_pk_mul_f32 v[74:75], v[18:19], v[20:21]
	v_pk_mul_f32 v[18:19], v[76:77], v[24:25]
	v_pk_add_f32 v[26:27], v[26:27], 1.0 op_sel_hi:[1,0]
	v_mul_f32_e32 v30, 0xbfb8aa3b, v30
	v_mul_f32_e32 v31, 0xbfb8aa3b, v31
	v_mul_f32_e32 v65, 0xbfb8aa3b, v65
	v_pk_mul_f32 v[68:69], v[24:25], v[24:25]
	v_pk_mul_f32 v[70:71], v[28:29], v[28:29]
	v_rcp_f32_e32 v24, v18
	v_rcp_f32_e32 v25, v19
	v_pk_mul_f32 v[28:29], v[26:27], v[28:29]
	v_exp_f32_e32 v30, v30
	v_exp_f32_e32 v31, v31
	v_exp_f32_e32 v65, v65
	v_rcp_f32_e32 v28, v28
	v_rcp_f32_e32 v29, v29
	v_pk_mul_f32 v[18:19], v[66:67], v[20:21]
	v_pk_mul_f32 v[20:21], v[76:77], v[24:25]
	v_pk_mul_f32 v[24:25], v[68:69], v[24:25]
	v_pk_add_f32 v[64:65], v[64:65], 1.0 op_sel_hi:[1,0]
	v_cvt_pk_f16_f32 v18, v18, v19
	v_cvt_pk_f16_f32 v19, v24, v25
	v_pk_mul_f32 v[24:25], v[26:27], v[28:29]
	v_pk_add_f32 v[26:27], v[30:31], 1.0 op_sel_hi:[1,0]
	v_cvt_pk_f16_f32 v23, v20, v21
	v_pk_mul_f32 v[20:21], v[26:27], v[64:65]
	v_pk_mul_f32 v[72:73], v[64:65], v[64:65]
	v_rcp_f32_e32 v30, v20
	v_rcp_f32_e32 v31, v21
	v_pk_mul_f32 v[20:21], v[70:71], v[28:29]
	v_cvt_pk_f16_f32 v22, v74, v75
	v_cvt_pk_f16_f32 v20, v20, v21
	v_pk_mul_f32 v[28:29], v[72:73], v[30:31]
	v_pk_mul_f32 v[26:27], v[26:27], v[30:31]
	v_cvt_pk_f16_f32 v21, v28, v29
	v_add_co_u32_e32 v28, vcc, s72, v16
	v_cvt_pk_f16_f32 v24, v24, v25
	s_nop 0
	v_addc_co_u32_e32 v29, vcc, 0, v17, vcc
	global_store_dwordx4 v[28:29], v[18:21], off sc1 nt
	v_cvt_pk_f16_f32 v25, v26, v27
	v_fmamk_f32 v27, v48, 0x3a000000, v0
	v_add_co_u32_e32 v18, vcc, s70, v16
	v_fmamk_f32 v21, v53, 0x3a000000, v9
	s_nop 0
	v_addc_co_u32_e32 v19, vcc, 0, v17, vcc
	global_store_dwordx4 v[18:19], v[22:25], off sc1 nt
	v_fmamk_f32 v19, v52, 0x3a000000, v8
	v_mul_f32_e32 v19, 0xbfb8aa3b, v19
	v_fmamk_f32 v18, v60, 0x3a000000, v12
	v_exp_f32_e32 v20, v19
	v_fmamk_f32 v19, v61, 0x3a000000, v13
	v_mul_f32_e32 v18, 0xbfb8aa3b, v18
	v_mul_f32_e32 v19, 0xbfb8aa3b, v19
	v_mul_f32_e32 v21, 0xbfb8aa3b, v21
	v_exp_f32_e32 v18, v18
	v_exp_f32_e32 v19, v19
	v_exp_f32_e32 v21, v21
	v_fmamk_f32 v23, v54, 0x3a000000, v10
	v_mul_f32_e32 v23, 0xbfb8aa3b, v23
	v_fmamk_f32 v22, v62, 0x3a000000, v14
	v_exp_f32_e32 v24, v23
	v_fmamk_f32 v23, v63, 0x3a000000, v15
	v_fmamk_f32 v25, v55, 0x3a000000, v11
	v_mul_f32_e32 v27, 0xbfb8aa3b, v27
	v_mul_f32_e32 v22, 0xbfb8aa3b, v22
	v_mul_f32_e32 v23, 0xbfb8aa3b, v23
	v_mul_f32_e32 v25, 0xbfb8aa3b, v25
	v_fmamk_f32 v26, v56, 0x3a000000, v4
	v_exp_f32_e32 v28, v27
	v_fmamk_f32 v27, v57, 0x3a000000, v5
	v_fmamk_f32 v29, v49, 0x3a000000, v1
	v_pk_add_f32 v[20:21], v[20:21], 1.0 op_sel_hi:[1,0]
	v_pk_add_f32 v[18:19], v[18:19], 1.0 op_sel_hi:[1,0]
	v_exp_f32_e32 v22, v22
	v_exp_f32_e32 v23, v23
	v_exp_f32_e32 v25, v25
	v_mul_f32_e32 v26, 0xbfb8aa3b, v26
	v_mul_f32_e32 v27, 0xbfb8aa3b, v27
; #define PG8_BAR __builtin_amdgcn_s_barrier()
; template <class Epi, class Sched, bool FP8 = false>
; __device__ __forceinline__ void gemm_phase(LAS unsigned char* lds, const Gemm g, const Sched& S, const Epi& E, const int tid) {
;     ...
;         cur = nxt; cA = nA; cB = nB; ++ui;
;         if (wr == 1) PG8_BAR;
;     __device__ __forceinline__ void operator()(const f32x4 (&acc)[2][2][4][2], const Unit& u, int wr, int wc, int fr, int fq) const {
;     ...
;         for (int ai = 0; ai < 2; ++ai)
; #pragma unroll
;             for (int m = 0; m < 4; ++m) {
;                 h16* rowp = PG + (size_t)(u.pm * 32 + u.pn) * 65536 + (ai * 4 + m) * 4096 + (wr * 4 + wc) * 512 + (fq * 16 + fr) * 8;
;                 float r[8], sg[8];
; #pragma unroll
;                 for (int n = 0; n < 2; ++n)
; #pragma unroll
;                     for (int j = 0; j < 4; ++j) { const float ea = __expf(-(acc[ai][0][m][n][j] * DS + ba[n][j])), eb = __expf(-(acc[ai][1][m][n][j] * DS + bb[n][j]));
;                         const float pa = 1.f + ea, pb = 1.f + eb, rp = __builtin_amdgcn_rcpf(pa * pb);
;                         sg[4 * n + j] = pa * rp; r[4 * n + j] = pb * pb * rp; }
;                 u32x4 w; w.x = pkh(r[0], r[1]); w.y = pkh(r[2], r[3]); w.z = pkh(r[4], r[5]); w.w = pkh(r[6], r[7]);
;                 *(u32x4*)rowp = w;
;                 w.x = pkh(sg[0], sg[1]); w.y = pkh(sg[2], sg[3]); w.z = pkh(sg[4], sg[5]); w.w = pkh(sg[6], sg[7]);
;                 *(u32x4*)(rowp + 32768) = w; }
	v_mul_f32_e32 v29, 0xbfb8aa3b, v29
	v_fmamk_f32 v31, v50, 0x3a000000, v2
	v_fmamk_f32 v49, v51, 0x3a000000, v3
	v_pk_mul_f32 v[50:51], v[20:21], v[20:21]
	v_pk_mul_f32 v[20:21], v[18:19], v[20:21]
	v_exp_f32_e32 v26, v26
	v_exp_f32_e32 v27, v27
	v_exp_f32_e32 v29, v29
	v_rcp_f32_e32 v20, v20
	v_rcp_f32_e32 v21, v21
	v_mul_f32_e32 v31, 0xbfb8aa3b, v31
	v_pk_add_f32 v[24:25], v[24:25], 1.0 op_sel_hi:[1,0]
	v_pk_add_f32 v[60:61], v[22:23], 1.0 op_sel_hi:[1,0]
	v_fmamk_f32 v30, v58, 0x3a000000, v6
	v_exp_f32_e32 v48, v31
	v_fmamk_f32 v31, v59, 0x3a000000, v7
	v_pk_add_f32 v[28:29], v[28:29], 1.0 op_sel_hi:[1,0]
	v_pk_mul_f32 v[58:59], v[18:19], v[20:21]
	v_pk_mul_f32 v[18:19], v[60:61], v[24:25]
	v_pk_add_f32 v[26:27], v[26:27], 1.0 op_sel_hi:[1,0]
	v_mul_f32_e32 v30, 0xbfb8aa3b, v30
	v_mul_f32_e32 v31, 0xbfb8aa3b, v31
	v_mul_f32_e32 v49, 0xbfb8aa3b, v49
	v_pk_mul_f32 v[52:53], v[24:25], v[24:25]
	v_pk_mul_f32 v[54:55], v[28:29], v[28:29]
	v_rcp_f32_e32 v24, v18
	v_rcp_f32_e32 v25, v19
	v_pk_mul_f32 v[28:29], v[26:27], v[28:29]
	v_exp_f32_e32 v30, v30
	v_exp_f32_e32 v31, v31
	v_exp_f32_e32 v49, v49
	v_rcp_f32_e32 v28, v28
	v_rcp_f32_e32 v29, v29
	v_pk_mul_f32 v[18:19], v[50:51], v[20:21]
	v_pk_mul_f32 v[20:21], v[60:61], v[24:25]
	v_pk_mul_f32 v[24:25], v[52:53], v[24:25]
	v_pk_add_f32 v[48:49], v[48:49], 1.0 op_sel_hi:[1,0]
	v_cvt_pk_f16_f32 v18, v18, v19
	v_cvt_pk_f16_f32 v19, v24, v25
	v_pk_mul_f32 v[24:25], v[26:27], v[28:29]
	v_pk_add_f32 v[26:27], v[30:31], 1.0 op_sel_hi:[1,0]
	v_cvt_pk_f16_f32 v23, v20, v21
	v_pk_mul_f32 v[20:21], v[26:27], v[48:49]
	v_pk_mul_f32 v[56:57], v[48:49], v[48:49]
	v_rcp_f32_e32 v30, v20
	v_rcp_f32_e32 v31, v21
	v_pk_mul_f32 v[20:21], v[54:55], v[28:29]
	v_fmamk_f32 v4, v40, 0x3a000000, v4
	v_cvt_pk_f16_f32 v20, v20, v21
	v_pk_mul_f32 v[28:29], v[56:57], v[30:31]
	v_pk_mul_f32 v[26:27], v[26:27], v[30:31]
	v_cvt_pk_f16_f32 v21, v28, v29
	v_add_co_u32_e32 v28, vcc, s76, v16
	v_cvt_pk_f16_f32 v22, v58, v59
	s_nop 0
	v_addc_co_u32_e32 v29, vcc, 0, v17, vcc
	global_store_dwordx4 v[28:29], v[18:21], off sc1 nt
	v_cvt_pk_f16_f32 v24, v24, v25
	v_cvt_pk_f16_f32 v25, v26, v27
	v_add_co_u32_e32 v18, vcc, s73, v16
	v_fmamk_f32 v12, v44, 0x3a000000, v12
	s_nop 0
	v_addc_co_u32_e32 v19, vcc, 0, v17, vcc
	v_fmamk_f32 v8, v36, 0x3a000000, v8
	v_fmamk_f32 v13, v45, 0x3a000000, v13
	v_fmamk_f32 v9, v37, 0x3a000000, v9
	v_mul_f32_e32 v4, 0xbfb8aa3b, v4
	v_fmamk_f32 v0, v32, 0x3a000000, v0
	v_fmamk_f32 v1, v33, 0x3a000000, v1
	global_store_dwordx4 v[18:19], v[22:25], off sc1 nt
	v_mul_f32_e32 v12, 0xbfb8aa3b, v12
	v_mul_f32_e32 v8, 0xbfb8aa3b, v8
	v_mul_f32_e32 v13, 0xbfb8aa3b, v13
	v_mul_f32_e32 v9, 0xbfb8aa3b, v9
	v_exp_f32_e32 v18, v4
	v_mul_f32_e32 v0, 0xbfb8aa3b, v0
	v_fmamk_f32 v4, v41, 0x3a000000, v5
	v_mul_f32_e32 v1, 0xbfb8aa3b, v1
	v_exp_f32_e32 v12, v12
	v_exp_f32_e32 v8, v8
	v_exp_f32_e32 v13, v13
	v_exp_f32_e32 v9, v9
	v_exp_f32_e32 v0, v0
	v_mul_f32_e32 v4, 0xbfb8aa3b, v4
	v_exp_f32_e32 v1, v1
	v_exp_f32_e32 v19, v4
	v_fmamk_f32 v4, v42, 0x3a000000, v6
	v_mul_f32_e32 v4, 0xbfb8aa3b, v4
	v_fmac_f32_e32 v7, 0x3a000000, v43
	v_fmamk_f32 v14, v46, 0x3a000000, v14
	v_fmamk_f32 v10, v38, 0x3a000000, v10
	v_fmac_f32_e32 v15, 0x3a000000, v47
	v_fmac_f32_e32 v11, 0x3a000000, v39
	v_exp_f32_e32 v6, v4
	v_mul_f32_e32 v4, 0xbfb8aa3b, v7
	v_mul_f32_e32 v14, 0xbfb8aa3b, v14
	v_mul_f32_e32 v10, 0xbfb8aa3b, v10
	v_mul_f32_e32 v15, 0xbfb8aa3b, v15
	v_mul_f32_e32 v11, 0xbfb8aa3b, v11
	v_exp_f32_e32 v7, v4
	v_pk_add_f32 v[4:5], v[8:9], 1.0 op_sel_hi:[1,0]
	v_pk_add_f32 v[22:23], v[0:1], 1.0 op_sel_hi:[1,0]
	v_pk_add_f32 v[0:1], v[12:13], 1.0 op_sel_hi:[1,0]
	v_exp_f32_e32 v14, v14
	v_exp_f32_e32 v10, v10
	v_exp_f32_e32 v15, v15
	v_exp_f32_e32 v11, v11
	v_pk_mul_f32 v[8:9], v[4:5], v[4:5]
	v_pk_mul_f32 v[4:5], v[0:1], v[4:5]
	v_pk_add_f32 v[14:15], v[14:15], 1.0 op_sel_hi:[1,0]
	v_rcp_f32_e32 v4, v4
	v_rcp_f32_e32 v5, v5
	v_pk_add_f32 v[10:11], v[10:11], 1.0 op_sel_hi:[1,0]
	v_fmamk_f32 v2, v34, 0x3a000000, v2
	v_pk_mul_f32 v[20:21], v[10:11], v[10:11]
	v_pk_mul_f32 v[26:27], v[0:1], v[4:5]
	v_pk_mul_f32 v[0:1], v[14:15], v[10:11]
	v_fmac_f32_e32 v3, 0x3a000000, v35
	v_rcp_f32_e32 v10, v0
	v_rcp_f32_e32 v11, v1
	v_mul_f32_e32 v2, 0xbfb8aa3b, v2
	v_mul_f32_e32 v3, 0xbfb8aa3b, v3
	v_exp_f32_e32 v2, v2
	v_exp_f32_e32 v3, v3
	v_pk_mul_f32 v[0:1], v[8:9], v[4:5]
	v_pk_mul_f32 v[8:9], v[14:15], v[10:11]
	v_pk_add_f32 v[14:15], v[18:19], 1.0 op_sel_hi:[1,0]
	v_pk_mul_f32 v[10:11], v[20:21], v[10:11]
	v_pk_mul_f32 v[18:19], v[14:15], v[22:23]
	v_pk_add_f32 v[2:3], v[2:3], 1.0 op_sel_hi:[1,0]
	v_rcp_f32_e32 v18, v18
	v_rcp_f32_e32 v19, v19
	v_cvt_pk_f16_f32 v0, v0, v1
	v_cvt_pk_f16_f32 v1, v10, v11
	v_pk_add_f32 v[10:11], v[6:7], 1.0 op_sel_hi:[1,0]
	v_pk_mul_f32 v[24:25], v[2:3], v[2:3]
	v_pk_mul_f32 v[2:3], v[10:11], v[2:3]
	v_cvt_pk_f16_f32 v5, v8, v9
	v_pk_mul_f32 v[8:9], v[14:15], v[18:19]
	v_rcp_f32_e32 v14, v2
	v_rcp_f32_e32 v15, v3
	v_pk_mul_f32 v[12:13], v[22:23], v[22:23]
	v_cvt_pk_f16_f32 v6, v8, v9
	v_pk_mul_f32 v[2:3], v[12:13], v[18:19]
	v_pk_mul_f32 v[8:9], v[10:11], v[14:15]
	v_pk_mul_f32 v[10:11], v[24:25], v[14:15]
	v_cvt_pk_f16_f32 v2, v2, v3
	v_cvt_pk_f16_f32 v3, v10, v11
	v_add_co_u32_e32 v10, vcc, 0xe000, v16
	v_cvt_pk_f16_f32 v4, v26, v27
	s_nop 0
	v_addc_co_u32_e32 v11, vcc, 0, v17, vcc
	global_store_dwordx4 v[10:11], v[0:3], off sc1 nt
	v_cvt_pk_f16_f32 v7, v8, v9
	s_nop 0
	v_add_co_u32_e32 v0, vcc, 0x1e000, v16
	s_nop 1
	v_addc_co_u32_e32 v1, vcc, 0, v17, vcc
	s_andn2_b64 vcc, exec, s[0:1]
	s_mov_b64 s[0:1], -1
	global_store_dwordx4 v[0:1], v[4:7], off sc1 nt
	s_cbranch_vccnz .LBB0_149
	s_andn2_b64 vcc, exec, s[4:5]
	s_cbranch_vccnz .LBB0_148
	s_barrier
	s_branch .LBB0_148

; #define LAS __attribute__((address_space(3)))
; #define H1_FLUSH(itp) do { h16* Lp_ = P.L + (size_t)(itp) * (HD * HD); \
;         _Pragma("unroll") for (int rep = 0; rep < 4; ++rep) { const int cidx = tid + 512 * rep; *(h16x8*)(Lp_ + cidx * 8) = *(const LAS h16x8*)(LT + cidx * 8); } } while (0)
; __device__ __forceinline__ void h1_phase(const Ptrs& P, LAS unsigned char* lds, int bx, int G, int tid) {
;     ...
;         float v0[8], v1[8];
; #pragma unroll
;         for (int u = 0; u < 8; ++u) { v0[u] = kk[u] * base * __builtin_amdgcn_rcpf(pc[u]); v1[u] = kk[8 + u] * base * __builtin_amdgcn_rcpf(pc[8 + u]); }
;         *(LAS bf16x8*)(KT + d * 72 + 16 * i) = mk_bf16x8(v0);
;         *(LAS bf16x8*)(KT + d * 72 + 16 * i + 8) = mk_bf16x8(v1);
;         if (i == 0) P.Dn[(size_t)it * HD + d] = base;
;         if (itprev >= 0) H1_FLUSH(itprev);
.LBB0_227:
	v_rcp_f32_e32 v68, v51
	v_rcp_f32_e32 v69, v52
	v_rcp_f32_e32 v70, v55
	v_rcp_f32_e32 v71, v56
	v_rcp_f32_e32 v50, v50
	v_rcp_f32_e32 v51, v9
	v_rcp_f32_e32 v52, v53
	v_rcp_f32_e32 v53, v54
	v_pk_mul_f32 v[0:1], v[0:1], v[8:9] op_sel_hi:[1,0]
	v_pk_mul_f32 v[6:7], v[6:7], v[8:9] op_sel_hi:[1,0]
	v_pk_mul_f32 v[2:3], v[2:3], v[8:9] op_sel_hi:[1,0]
	v_pk_mul_f32 v[4:5], v[4:5], v[8:9] op_sel_hi:[1,0]
	v_pk_mul_f32 v[0:1], v[68:69], v[0:1]
	v_pk_mul_f32 v[6:7], v[70:71], v[6:7]
	v_pk_mul_f32 v[12:13], v[12:13], v[8:9] op_sel_hi:[1,0]
	v_pk_mul_f32 v[10:11], v[10:11], v[8:9] op_sel_hi:[1,0]
	v_pk_mul_f32 v[14:15], v[14:15], v[8:9] op_sel_hi:[1,0]
	v_pk_mul_f32 v[32:33], v[32:33], v[8:9] op_sel_hi:[1,0]
	v_pk_mul_f32 v[2:3], v[50:51], v[2:3]
	v_pk_mul_f32 v[4:5], v[52:53], v[4:5]
	v_bfe_u32 v9, v7, 16, 1
	v_bfe_u32 v50, v6, 16, 1
	v_bfe_u32 v51, v1, 16, 1
	v_bfe_u32 v52, v0, 16, 1
	v_rcp_f32_e32 v58, v58
	v_rcp_f32_e32 v67, v59
	v_rcp_f32_e32 v59, v60
	v_rcp_f32_e32 v60, v61
	v_rcp_f32_e32 v62, v62
	v_rcp_f32_e32 v61, v63
	v_rcp_f32_e32 v63, v64
	v_add3_u32 v0, v0, v52, s49
	v_add3_u32 v1, v1, v51, s49
	v_add3_u32 v6, v6, v50, s49
	v_add3_u32 v7, v7, v9, s49
	v_bfe_u32 v9, v2, 16, 1
	v_bfe_u32 v50, v3, 16, 1
	v_bfe_u32 v51, v4, 16, 1
	v_bfe_u32 v52, v5, 16, 1
	v_rcp_f32_e32 v66, v57
	v_add3_u32 v5, v5, v52, s49
	v_add3_u32 v4, v4, v51, s49
	v_add3_u32 v3, v3, v50, s49
	v_add3_u32 v2, v2, v9, s49
	v_lshrrev_b32_e32 v9, 16, v2
	v_lshrrev_b32_e32 v50, 16, v3
	v_lshrrev_b32_e32 v2, 16, v4
	v_lshrrev_b32_e32 v3, 16, v5
	v_and_or_b32 v3, v7, s50, v3
	v_and_or_b32 v2, v6, s50, v2
	v_and_or_b32 v1, v1, s50, v50
	v_and_or_b32 v0, v0, s50, v9
	ds_write_b128 v47, v[0:3]
	v_pk_mul_f32 v[2:3], v[58:59], v[10:11]
	v_pk_mul_f32 v[6:7], v[62:63], v[32:33]
	v_pk_mul_f32 v[0:1], v[66:67], v[12:13]
	v_pk_mul_f32 v[4:5], v[60:61], v[14:15]
	v_bfe_u32 v9, v7, 16, 1
	v_bfe_u32 v10, v6, 16, 1
	v_bfe_u32 v11, v3, 16, 1
	v_bfe_u32 v12, v2, 16, 1
	v_add3_u32 v12, v2, v12, s49
	v_add3_u32 v11, v3, v11, s49
	v_add3_u32 v2, v6, v10, s49
	v_add3_u32 v3, v7, v9, s49
	v_bfe_u32 v6, v0, 16, 1
	v_bfe_u32 v7, v1, 16, 1
	v_bfe_u32 v9, v4, 16, 1
	v_bfe_u32 v10, v5, 16, 1
	v_add3_u32 v5, v5, v10, s49
	v_add3_u32 v4, v4, v9, s49
	v_add3_u32 v1, v1, v7, s49
	v_add3_u32 v0, v0, v6, s49
	v_lshrrev_b32_e32 v0, 16, v0
	v_lshrrev_b32_e32 v1, 16, v1
	v_lshrrev_b32_e32 v4, 16, v4
	v_lshrrev_b32_e32 v5, 16, v5
	v_and_or_b32 v3, v3, s50, v5
	v_and_or_b32 v2, v2, s50, v4
	v_and_or_b32 v1, v11, s50, v1
	v_and_or_b32 v0, v12, s50, v0
	s_andn2_b64 vcc, exec, s[16:17]
	ds_write_b128 v47, v[0:3] offset:16
	s_cbranch_vccnz .LBB0_229
	global_store_dword v[30:31], v8, off sc1
.LBB0_229:
	s_cmp_lt_i32 s8, 0
	s_cbranch_scc1 .LBB0_231
	ds_read_b128 v[0:3], v42 offset:55296
	ds_read_b128 v[4:7], v42 offset:63488
	s_lshl_b64 s[54:55], s[8:9], 15
	s_add_u32 s54, s29, s54
	s_addc_u32 s55, s44, s55
	v_lshl_add_u64 v[8:9], v[16:17], 1, s[54:55]
	s_waitcnt lgkmcnt(1)
	global_store_dwordx4 v[8:9], v[0:3], off sc1
	ds_read_b128 v[0:3], v39 offset:16384
	ds_read_b128 v[8:11], v39 offset:24576
	v_lshl_add_u64 v[12:13], v[26:27], 1, s[54:55]
	s_waitcnt lgkmcnt(2)
	global_store_dwordx4 v[12:13], v[4:7], off sc1
	s_nop 1
	v_lshl_add_u64 v[4:5], v[24:25], 1, s[54:55]
	s_waitcnt lgkmcnt(1)
	global_store_dwordx4 v[4:5], v[0:3], off sc1
	s_nop 1
	v_lshl_add_u64 v[0:1], v[28:29], 1, s[54:55]
	s_waitcnt lgkmcnt(0)
	global_store_dwordx4 v[0:1], v[8:11], off sc1
; #define LAS __attribute__((address_space(3)))
; #define H1_PREFETCH(itn) do { const int n_ = (itn) >> 4, h_ = (itn) & 15; const h16* base_ = P.PA + (size_t)(n_ * CH) * 8192 + h_ * HD; \
;         tile_ld(base_ + HW, pf, tid); tile_ld(base_ + 2 * HW, pv, tid); } while (0)
; #define H1_FLUSH(itp) do { h16* Lp_ = P.L + (size_t)(itp) * (HD * HD); \
;         _Pragma("unroll") for (int rep = 0; rep < 4; ++rep) { const int cidx = tid + 512 * rep; *(h16x8*)(Lp_ + cidx * 8) = *(const LAS h16x8*)(LT + cidx * 8); } } while (0)
; __device__ __forceinline__ void h1_phase(const Ptrs& P, LAS unsigned char* lds, int bx, int G, int tid) {
;     ...
;         { const int nit = it + G; H1_PREFETCH(nit < NIT ? nit : it); }
;         __syncthreads();
;         f32x4 acc[8];
; #pragma unroll
;         for (int nn = 0; nn < 8; ++nn) acc[nn] = (f32x4){0.f, 0.f, 0.f, 0.f};
; #pragma unroll
;         for (int k2 = 0; k2 < 2; ++k2) {
;             const bf16x8 a = *(const LAS bf16x8*)(VT + vt_idx(16 * w + fr, 32 * k2 + 8 * fq));
; #pragma unroll
;             for (int nn = 0; nn < 8; ++nn) { const bf16x8 b = *(const LAS bf16x8*)(KT + (16 * nn + fr) * 72 + 32 * k2 + 8 * fq);
;                 acc[nn] = __builtin_amdgcn_mfma_f32_16x16x32_bf16(a, b, acc[nn], 0, 0, 0); }
;         }
; #pragma unroll
;         for (int nn = 0; nn < 8; ++nn)
; #pragma unroll
;             for (int j = 0; j < 4; ++j) LT[(16 * w + 4 * fq + j) * HD + 16 * nn + fr] = (h16)acc[nn][j];
;         itprev = it;
;         __syncthreads();
;     }
;     if (itprev >= 0) H1_FLUSH(itprev);
.LBB0_231:
	s_add_i32 s51, s26, s30
	s_cmpk_lt_i32 s51, 0x800
	s_cselect_b32 s8, s51, s26
	s_lshl_b32 s53, s8, 2
	s_and_b32 s54, s53, 0xffffffc0
	s_ashr_i32 s55, s54, 31
	s_lshl_b64 s[54:55], s[54:55], 14
	s_add_u32 s53, s27, s54
	s_addc_u32 s55, s45, s55
	s_lshl_b32 s8, s8, 8
	s_and_b32 s8, s8, 0xf00
	s_add_u32 s54, s53, s8
	s_addc_u32 s55, s55, 0
	v_lshl_add_u64 v[0:1], s[54:55], 0, v[18:19]
	v_lshl_add_u64 v[2:3], v[0:1], 0, s[12:13]
	v_lshl_add_u64 v[4:5], v[2:3], 0, v[20:21]
	v_lshl_add_u64 v[2:3], v[2:3], 0, v[22:23]
	v_lshl_add_u64 v[0:1], v[0:1], 0, s[14:15]
	global_load_dwordx4 v[8:11], v[4:5], off
	global_load_dwordx4 v[12:15], v[2:3], off
	v_lshl_add_u64 v[2:3], v[0:1], 0, v[20:21]
	v_lshl_add_u64 v[0:1], v[0:1], 0, v[22:23]
	global_load_dwordx4 v[4:7], v[2:3], off
	s_nop 0
	global_load_dwordx4 v[0:3], v[0:1], off
	s_waitcnt lgkmcnt(0)
	s_barrier
	ds_read_b128 v[50:53], v43 offset:18432
	ds_read_b128 v[54:57], v48
	ds_read_b128 v[58:61], v44 offset:18432
	ds_read_b128 v[62:65], v48 offset:64
	s_waitcnt lgkmcnt(2)
	v_mfma_f32_16x16x32_bf16 v[54:57], v[50:53], v[54:57], 0
	ds_read_b128 v[66:69], v48 offset:2304
	ds_read_b128 v[70:73], v48 offset:2368
	ds_read_b128 v[74:77], v48 offset:4608
	ds_read_b128 v[78:81], v48 offset:4672
	ds_read_b128 v[82:85], v48 offset:6912
	ds_read_b128 v[86:89], v48 offset:6976
	s_waitcnt lgkmcnt(5)
	v_mfma_f32_16x16x32_bf16 v[66:69], v[50:53], v[66:69], 0
	ds_read_b128 v[90:93], v48 offset:9216
	ds_read_b128 v[94:97], v48 offset:9280
	ds_read_b128 v[98:101], v48 offset:11520
	ds_read_b128 v[102:105], v48 offset:11584
	ds_read_b128 v[106:109], v48 offset:13824
	ds_read_b128 v[110:113], v48 offset:13888
	v_mfma_f32_16x16x32_bf16 v[54:57], v[58:61], v[62:65], v[54:57]
	ds_read_b128 v[114:117], v48 offset:16128
	ds_read_b128 v[118:121], v48 offset:16192
	s_add_i32 s46, s46, s48
	s_cmpk_gt_i32 s51, 0x7ff
	s_waitcnt lgkmcnt(11)
	v_mfma_f32_16x16x32_bf16 v[74:77], v[50:53], v[74:77], 0
	s_nop 1
	v_cvt_f16_f32_e32 v32, v54
	v_cvt_f16_f32_e32 v33, v55
	v_cvt_f16_f32_e32 v54, v56
	v_mfma_f32_16x16x32_bf16 v[62:65], v[58:61], v[70:73], v[66:69]
	v_cvt_f16_f32_e32 v55, v57
	ds_write_b16 v49, v32 offset:55296
	ds_write_b16 v49, v33 offset:55552
	ds_write_b16 v49, v54 offset:55808
	ds_write_b16 v49, v55 offset:56064
	v_lshl_add_u64 v[30:31], v[30:31], 0, s[24:25]
	s_waitcnt lgkmcnt(13)
	v_mfma_f32_16x16x32_bf16 v[82:85], v[50:53], v[82:85], 0
	v_cvt_f16_f32_e32 v32, v62
	v_cvt_f16_f32_e32 v33, v63
	v_cvt_f16_f32_e32 v54, v64
	v_mfma_f32_16x16x32_bf16 v[66:69], v[58:61], v[78:81], v[74:77]
	v_cvt_f16_f32_e32 v55, v65
	ds_write_b16 v49, v32 offset:55328
	ds_write_b16 v49, v33 offset:55584
	ds_write_b16 v49, v54 offset:55840
	ds_write_b16 v49, v55 offset:56096
	s_nop 2
	v_cvt_f16_f32_e32 v32, v66
	s_waitcnt lgkmcnt(14)
	v_mfma_f32_16x16x32_bf16 v[90:93], v[50:53], v[90:93], 0
	v_cvt_f16_f32_e32 v33, v67
	v_cvt_f16_f32_e32 v54, v68
	v_cvt_f16_f32_e32 v55, v69
	v_mfma_f32_16x16x32_bf16 v[70:73], v[58:61], v[86:89], v[82:85]
	ds_write_b16 v49, v32 offset:55360
	ds_write_b16 v49, v33 offset:55616
	ds_write_b16 v49, v54 offset:55872
	ds_write_b16 v49, v55 offset:56128
	s_waitcnt lgkmcnt(14)
	v_mfma_f32_16x16x32_bf16 v[98:101], v[50:53], v[98:101], 0
	s_nop 1
	v_cvt_f16_f32_e32 v32, v70
	v_cvt_f16_f32_e32 v33, v71
	v_cvt_f16_f32_e32 v54, v72
	v_mfma_f32_16x16x32_bf16 v[74:77], v[58:61], v[94:97], v[90:93]
	v_cvt_f16_f32_e32 v55, v73
	ds_write_b16 v49, v32 offset:55392
	ds_write_b16 v49, v33 offset:55648
	ds_write_b16 v49, v54 offset:55904
	ds_write_b16 v49, v55 offset:56160
	s_nop 2
	v_cvt_f16_f32_e32 v32, v74
	v_mfma_f32_16x16x32_bf16 v[106:109], v[50:53], v[106:109], 0
	v_cvt_f16_f32_e32 v33, v75
	v_cvt_f16_f32_e32 v54, v76
	v_cvt_f16_f32_e32 v55, v77
	v_mfma_f32_16x16x32_bf16 v[78:81], v[58:61], v[102:105], v[98:101]
	ds_write_b16 v49, v32 offset:55424
	ds_write_b16 v49, v33 offset:55680
	ds_write_b16 v49, v54 offset:55936
	ds_write_b16 v49, v55 offset:56192
	s_waitcnt lgkmcnt(14)
	v_mfma_f32_16x16x32_bf16 v[50:53], v[50:53], v[114:117], 0
	s_nop 1
	v_cvt_f16_f32_e32 v32, v78
	v_cvt_f16_f32_e32 v33, v79
	v_cvt_f16_f32_e32 v54, v80
	v_mfma_f32_16x16x32_bf16 v[82:85], v[58:61], v[110:113], v[106:109]
	v_cvt_f16_f32_e32 v55, v81
	ds_write_b16 v49, v32 offset:55456
	ds_write_b16 v49, v33 offset:55712
	ds_write_b16 v49, v54 offset:55968
	ds_write_b16 v49, v55 offset:56224
	s_nop 2
	v_cvt_f16_f32_e32 v32, v82
	v_mfma_f32_16x16x32_bf16 v[50:53], v[58:61], v[118:121], v[50:53]
	v_cvt_f16_f32_e32 v33, v83
	v_cvt_f16_f32_e32 v54, v84
	v_cvt_f16_f32_e32 v55, v85
	ds_write_b16 v49, v32 offset:55488
	ds_write_b16 v49, v33 offset:55744
	ds_write_b16 v49, v54 offset:56000
	ds_write_b16 v49, v55 offset:56256
	s_nop 0
	v_cvt_f16_f32_e32 v32, v50
	v_cvt_f16_f32_e32 v33, v51
	v_cvt_f16_f32_e32 v50, v52
	v_cvt_f16_f32_e32 v51, v53
	ds_write_b16 v49, v32 offset:55520
	ds_write_b16 v49, v33 offset:55776
	ds_write_b16 v49, v50 offset:56032
	ds_write_b16 v49, v51 offset:56288
	s_waitcnt lgkmcnt(0)
	s_barrier
	s_cbranch_scc0 .LBB0_219
	s_cmp_gt_i32 s26, -1
	s_cbranch_scc0 .LBB0_234
	s_mov_b32 s27, 0
	s_waitcnt vmcnt(0)
	ds_read_b128 v[0:3], v42 offset:55296
	ds_read_b128 v[4:7], v42 offset:63488
	s_lshl_b64 s[8:9], s[26:27], 15
	s_add_u32 s8, s29, s8
	s_addc_u32 s9, s44, s9
	v_lshl_add_u64 v[8:9], v[16:17], 1, s[8:9]
	s_waitcnt lgkmcnt(1)
	global_store_dwordx4 v[8:9], v[0:3], off sc1
	ds_read_b128 v[0:3], v39 offset:16384
	ds_read_b128 v[8:11], v39 offset:24576
	v_lshl_add_u64 v[12:13], v[26:27], 1, s[8:9]
	s_waitcnt lgkmcnt(2)
	global_store_dwordx4 v[12:13], v[4:7], off sc1
	s_nop 1
	v_lshl_add_u64 v[4:5], v[24:25], 1, s[8:9]
	s_waitcnt lgkmcnt(1)
	global_store_dwordx4 v[4:5], v[0:3], off sc1
	s_nop 1
	v_lshl_add_u64 v[0:1], v[28:29], 1, s[8:9]
	s_waitcnt lgkmcnt(0)
	global_store_dwordx4 v[0:1], v[8:11], off sc1

; __device__ __forceinline__ void yb_phase(const Ptrs& P, int G, int tid) {
;     ...
;         const int c = (it & 255) * 8, t0 = (it >> 8) * 8;
;         float w0[8], w1[8], w2[8], pm2[8], pm1[8];
; #pragma unroll
;         for (int q = 0; q < 2; ++q) { const f32x4 a = *(const f32x4*)(P.conv_w + c + 4 * q), b = *(const f32x4*)(P.conv_w + HW + c + 4 * q), cc = *(const f32x4*)(P.conv_w + 2 * HW + c + 4 * q);
; #pragma unroll
;             for (int j = 0; j < 4; ++j) { w0[4 * q + j] = a[j]; w1[4 * q + j] = b[j]; w2[4 * q + j] = cc[j]; } }
;         if (t0 > 0) { const h16x8 a = *(const h16x8*)(P.PP + (size_t)(t0 - 2) * HW + c), b = *(const h16x8*)(P.PP + (size_t)(t0 - 1) * HW + c);
; #pragma unroll
;             for (int j = 0; j < 8; ++j) { pm2[j] = (float)a[j]; pm1[j] = (float)b[j]; } }
;         else {
; #pragma unroll
;             for (int j = 0; j < 8; ++j) { pm2[j] = 0.f; pm1[j] = 0.f; } }
;         h16x8 pcv[8], ggv[8];
; #pragma unroll
;         for (int r = 0; r < 8; ++r) { pcv[r] = *(const h16x8*)(P.PP + (size_t)(t0 + r) * HW + c); ggv[r] = *(const h16x8*)(P.PGG + (size_t)(t0 + r) * HW + c); }
; #pragma unroll
;         for (int r = 0; r < 8; ++r) {
;             const h16x8 pc = pcv[r], gg = ggv[r];
;             float y[8];
; #pragma unroll
;             for (int j = 0; j < 8; ++j) { const float pcf = (float)pc[j]; y[j] = (float)gg[j] * (w0[j] * pm2[j] + w1[j] * pm1[j] + w2[j] * pcf); pm2[j] = pm1[j]; pm1[j] = pcf; }
.LBB0_236:
	s_or_b64 exec, exec, s[22:23]
	v_lshl_add_u64 v[28:29], s[10:11], 0, v[66:67]
	v_lshlrev_b64 v[32:33], 12, v[24:25]
	v_lshl_add_u64 v[34:35], v[28:29], 0, v[32:33]
	v_lshl_add_u64 v[30:31], s[12:13], 0, v[66:67]
	global_load_dwordx4 v[56:59], v[34:35], off
	v_or_b32_e32 v100, 1, v24
	v_lshl_add_u64 v[32:33], v[30:31], 0, v[32:33]
	v_ashrrev_i32_e32 v101, 31, v100
	global_load_dwordx4 v[112:115], v[32:33], off
	v_lshlrev_b64 v[32:33], 12, v[100:101]
	v_lshl_add_u64 v[34:35], v[28:29], 0, v[32:33]
	v_lshl_add_u64 v[32:33], v[30:31], 0, v[32:33]
	global_load_dwordx4 v[44:47], v[32:33], off
	global_load_dwordx4 v[48:51], v[34:35], off
	s_waitcnt vmcnt(8)
	v_mov_b32_e32 v116, v12
	s_waitcnt vmcnt(4)
	v_mov_b32_e32 v117, v16
	v_or_b32_e32 v102, 2, v24
	v_or_b32_e32 v98, 3, v24
	v_or_b32_e32 v96, 4, v24
	v_or_b32_e32 v86, 5, v24
	v_or_b32_e32 v84, 6, v24
	v_or_b32_e32 v68, 7, v26
	v_mov_b32_e32 v118, v12
	v_mov_b32_e32 v119, v20
	v_lshlrev_b64 v[24:25], 13, v[24:25]
	v_ashrrev_i32_e32 v103, 31, v102
	v_ashrrev_i32_e32 v99, 31, v98
	v_ashrrev_i32_e32 v97, 31, v96
	v_ashrrev_i32_e32 v87, 31, v86
	v_ashrrev_i32_e32 v85, 31, v84
	v_ashrrev_i32_e32 v69, 31, v68
	v_lshl_add_u64 v[24:25], s[14:15], 0, v[24:25]
	v_lshlrev_b64 v[26:27], 12, v[102:103]
	v_lshlrev_b64 v[32:33], 12, v[98:99]
	v_lshlrev_b64 v[34:35], 12, v[96:97]
	v_lshlrev_b64 v[36:37], 12, v[86:87]
	v_lshlrev_b64 v[38:39], 12, v[84:85]
	v_lshlrev_b64 v[40:41], 12, v[68:69]
	v_lshl_add_u64 v[120:121], v[24:25], 0, v[66:67]
	v_lshl_add_u64 v[24:25], v[28:29], 0, v[26:27]
	v_lshl_add_u64 v[122:123], v[30:31], 0, v[26:27]
	v_lshl_add_u64 v[26:27], v[28:29], 0, v[32:33]
	v_lshl_add_u64 v[124:125], v[30:31], 0, v[32:33]
	v_lshl_add_u64 v[32:33], v[28:29], 0, v[34:35]
	v_lshl_add_u64 v[126:127], v[30:31], 0, v[34:35]
	v_lshl_add_u64 v[34:35], v[28:29], 0, v[36:37]
	v_lshl_add_u64 v[130:131], v[28:29], 0, v[38:39]
	v_lshl_add_u64 v[28:29], v[28:29], 0, v[40:41]
	v_lshl_add_u64 v[128:129], v[30:31], 0, v[36:37]
	v_lshl_add_u64 v[132:133], v[30:31], 0, v[38:39]
	v_lshl_add_u64 v[134:135], v[30:31], 0, v[40:41]
	global_load_dwordx4 v[52:55], v[24:25], off
	global_load_dwordx4 v[40:43], v[26:27], off
	global_load_dwordx4 v[36:39], v[32:33], off
	s_nop 0
	global_load_dwordx4 v[24:27], v[34:35], off
	s_nop 0
	global_load_dwordx4 v[32:35], v[130:131], off
	s_nop 0
	global_load_dwordx4 v[28:31], v[28:29], off
	v_mov_b32_e32 v82, v13
	v_mov_b32_e32 v83, v17
	v_mov_b32_e32 v80, v14
	v_mov_b32_e32 v81, v18
	v_mov_b32_e32 v78, v15
	v_mov_b32_e32 v79, v19
	v_mov_b32_e32 v76, v0
	v_mov_b32_e32 v77, v4
	v_mov_b32_e32 v74, v1
	v_mov_b32_e32 v75, v5
	v_mov_b32_e32 v72, v2
	v_mov_b32_e32 v73, v6
	v_mov_b32_e32 v70, v3
	v_mov_b32_e32 v71, v7
	v_lshlrev_b64 v[100:101], 13, v[100:101]
	v_lshl_add_u64 v[100:101], s[14:15], 0, v[100:101]
	v_lshl_add_u64 v[100:101], v[100:101], 0, v[66:67]
	v_add_u32_e32 v108, s6, v108
	v_add_u32_e32 v109, s7, v109
	s_waitcnt vmcnt(9)
	v_cvt_f32_f16_e32 v105, v56
	v_cvt_f32_f16_sdwa v130, v56 dst_sel:DWORD dst_unused:UNUSED_PAD src0_sel:WORD_1
	v_cvt_f32_f16_e32 v136, v57
	s_waitcnt vmcnt(8)
	v_cvt_f32_f16_e32 v89, v112
	v_cvt_f32_f16_sdwa v111, v112 dst_sel:DWORD dst_unused:UNUSED_PAD src0_sel:WORD_1
	v_cvt_f32_f16_e32 v138, v113
	v_cvt_f32_f16_sdwa v140, v113 dst_sel:DWORD dst_unused:UNUSED_PAD src0_sel:WORD_1
	v_cvt_f32_f16_e32 v142, v114
	v_cvt_f32_f16_sdwa v144, v114 dst_sel:DWORD dst_unused:UNUSED_PAD src0_sel:WORD_1
	s_waitcnt vmcnt(7)
	v_cvt_f32_f16_e32 v114, v44
	v_pk_mul_f32 v[112:113], v[116:117], v[104:105]
	v_mov_b32_e32 v107, v105
	v_fma_f32 v112, v20, v106, v112
	v_pk_mul_f32 v[104:105], v[118:119], v[106:107]
	v_add_f32_e32 v106, v112, v113
	v_add_f32_e32 v104, v104, v105
	v_mul_f32_e32 v105, v106, v89
	s_waitcnt vmcnt(6)
	v_fma_mix_f32 v89, v16, v48, v104 op_sel_hi:[0,1,0]
	v_cvt_f32_f16_e32 v145, v115
	v_cvt_f32_f16_sdwa v146, v115 dst_sel:DWORD dst_unused:UNUSED_PAD src0_sel:WORD_1
	v_mul_f32_e32 v149, v89, v114
	global_load_dwordx4 v[112:115], v[122:123], off
	global_load_dwordx4 v[116:119], v[124:125], off
	v_mov_b32_e32 v89, v130
	v_pk_mul_f32 v[88:89], v[82:83], v[88:89]
	v_cvt_f32_f16_sdwa v131, v48 dst_sel:DWORD dst_unused:UNUSED_PAD src0_sel:WORD_1
	v_fma_f32 v88, v21, v91, v88
	v_add_f32_e32 v88, v88, v89
	v_mul_f32_e32 v88, v88, v111
	v_cvt_pk_bf16_f32 v104, v105, v88
	v_mov_b32_e32 v88, v21
	v_mov_b32_e32 v89, v17
	v_pk_mul_f32 v[106:107], v[88:89], v[130:131]
	v_cvt_f32_f16_sdwa v44, v44 dst_sel:DWORD dst_unused:UNUSED_PAD src0_sel:WORD_1
	v_fma_f32 v17, v13, v91, v106
	v_mov_b32_e32 v91, v136
	v_pk_mul_f32 v[90:91], v[80:81], v[90:91]
	v_cvt_f32_f16_e32 v137, v49
	v_fma_f32 v90, v22, v95, v90
	v_add_f32_e32 v90, v90, v91
	v_add_f32_e32 v17, v17, v107
	v_mul_f32_e32 v105, v90, v138
	v_cvt_f32_f16_sdwa v138, v57 dst_sel:DWORD dst_unused:UNUSED_PAD src0_sel:WORD_1
	v_mul_f32_e32 v17, v17, v44
	v_cvt_f32_f16_e32 v44, v45
	v_mov_b32_e32 v90, v22
	v_mov_b32_e32 v91, v18
	v_pk_mul_f32 v[106:107], v[90:91], v[136:137]
	v_cvt_f32_f16_sdwa v139, v49 dst_sel:DWORD dst_unused:UNUSED_PAD src0_sel:WORD_1
	v_fma_f32 v18, v14, v95, v106
	v_add_f32_e32 v18, v18, v107
	v_mov_b32_e32 v95, v138
	v_mul_f32_e32 v57, v18, v44
	v_cvt_f32_f16_sdwa v106, v45 dst_sel:DWORD dst_unused:UNUSED_PAD src0_sel:WORD_1
	v_pk_mul_f32 v[44:45], v[78:79], v[94:95]
	v_cvt_f32_f16_e32 v141, v50
	v_fma_f32 v18, v23, v93, v44
	v_add_f32_e32 v18, v18, v45
	v_mul_f32_e32 v18, v18, v140
	v_cvt_f32_f16_e32 v140, v58
	v_cvt_pk_bf16_f32 v105, v105, v18
	v_mov_b32_e32 v18, v23
	v_pk_mul_f32 v[44:45], v[18:19], v[138:139]
	v_mov_b32_e32 v94, v8
	v_fma_f32 v44, v15, v93, v44
	v_add_f32_e32 v44, v44, v45
; __device__ __forceinline__ void yb_phase(const Ptrs& P, int G, int tid) {
;     ...
;         for (int r = 0; r < 8; ++r) { pcv[r] = *(const h16x8*)(P.PP + (size_t)(t0 + r) * HW + c); ggv[r] = *(const h16x8*)(P.PGG + (size_t)(t0 + r) * HW + c); }
; #pragma unroll
;         for (int r = 0; r < 8; ++r) {
;             const h16x8 pc = pcv[r], gg = ggv[r];
;             float y[8];
; #pragma unroll
;             for (int j = 0; j < 8; ++j) { const float pcf = (float)pc[j]; y[j] = (float)gg[j] * (w0[j] * pm2[j] + w1[j] * pm1[j] + w2[j] * pcf); pm2[j] = pm1[j]; pm1[j] = pcf; }
;             u32x4 o; o.x = pkg(y[0], y[1]); o.y = pkg(y[2], y[3]); o.z = pkg(y[4], y[5]); o.w = pkg(y[6], y[7]);
;             *(u32x4*)(P.YAB + (size_t)(t0 + r) * D + HW + c) = o;
	v_mov_b32_e32 v93, v140
	v_mul_f32_e32 v111, v44, v106
	v_pk_mul_f32 v[44:45], v[76:77], v[92:93]
	v_cvt_f32_f16_e32 v106, v46
	v_fma_f32 v44, v8, v65, v44
	v_add_f32_e32 v44, v44, v45
	v_mul_f32_e32 v92, v44, v142
	v_cvt_f32_f16_sdwa v142, v58 dst_sel:DWORD dst_unused:UNUSED_PAD src0_sel:WORD_1
	v_mov_b32_e32 v95, v4
	v_pk_mul_f32 v[44:45], v[94:95], v[140:141]
	v_cvt_f32_f16_sdwa v143, v50 dst_sel:DWORD dst_unused:UNUSED_PAD src0_sel:WORD_1
	v_fma_f32 v4, v0, v65, v44
	v_mov_b32_e32 v65, v142
	v_add_f32_e32 v4, v4, v45
	v_pk_mul_f32 v[44:45], v[74:75], v[64:65]
	v_mul_f32_e32 v131, v4, v106
	v_fma_f32 v4, v9, v63, v44
	v_add_f32_e32 v4, v4, v45
	v_mul_f32_e32 v4, v4, v144
	v_cvt_f32_f16_e32 v124, v59
	v_cvt_f32_f16_sdwa v46, v46 dst_sel:DWORD dst_unused:UNUSED_PAD src0_sel:WORD_1
	v_cvt_pk_bf16_f32 v106, v92, v4
	v_mov_b32_e32 v4, v9
	v_pk_mul_f32 v[44:45], v[4:5], v[142:143]
	v_cvt_f32_f16_e32 v125, v51
	v_fma_f32 v44, v1, v63, v44
	v_add_f32_e32 v44, v44, v45
	v_mov_b32_e32 v63, v124
	v_mul_f32_e32 v137, v44, v46
	v_pk_mul_f32 v[44:45], v[72:73], v[62:63]
	v_cvt_f32_f16_sdwa v144, v59 dst_sel:DWORD dst_unused:UNUSED_PAD src0_sel:WORD_1
	v_fma_f32 v44, v10, v61, v44
	v_cvt_f32_f16_e32 v46, v47
	v_add_f32_e32 v44, v44, v45
	v_mov_b32_e32 v92, v10
	v_mov_b32_e32 v93, v6
	v_mul_f32_e32 v58, v44, v145
	v_pk_mul_f32 v[44:45], v[92:93], v[124:125]
	v_cvt_f32_f16_sdwa v139, v47 dst_sel:DWORD dst_unused:UNUSED_PAD src0_sel:WORD_1
	v_fma_f32 v6, v2, v61, v44
	v_mov_b32_e32 v61, v144
	v_add_f32_e32 v6, v6, v45
	v_pk_mul_f32 v[44:45], v[70:71], v[60:61]
	v_mul_f32_e32 v125, v6, v46
	v_fma_f32 v6, v11, v110, v44
	v_add_f32_e32 v6, v6, v45
	v_mul_f32_e32 v6, v6, v146
	v_add_co_u32_e32 v146, vcc, s24, v120
	v_cvt_pk_bf16_f32 v107, v58, v6
	v_cvt_f32_f16_sdwa v145, v51 dst_sel:DWORD dst_unused:UNUSED_PAD src0_sel:WORD_1
	s_nop 0
	v_addc_co_u32_e32 v147, vcc, 0, v121, vcc
	global_load_dwordx4 v[120:123], v[126:127], off
	global_load_dwordx4 v[62:65], v[128:129], off
	global_load_dwordx4 v[58:61], v[132:133], off
	global_load_dwordx4 v[44:47], v[134:135], off
	v_mov_b32_e32 v6, v11
	global_store_dwordx4 v[146:147], v[104:107], off sc1
	v_cvt_f32_f16_e32 v148, v48
	v_add_co_u32_e32 v100, vcc, s24, v100
	v_pk_mul_f32 v[104:105], v[6:7], v[144:145]
	s_nop 0
	v_addc_co_u32_e32 v101, vcc, 0, v101, vcc
	v_fma_f32 v104, v3, v110, v104
	v_add_f32_e32 v104, v104, v105
	v_mul_f32_e32 v107, v104, v139
	v_cvt_pk_bf16_f32 v104, v149, v17
	s_waitcnt vmcnt(12)
	v_cvt_f32_f16_e32 v17, v52
	v_cvt_pk_bf16_f32 v105, v57, v111
	v_cvt_pk_bf16_f32 v106, v131, v137
	v_cvt_pk_bf16_f32 v107, v125, v107
	global_store_dwordx4 v[100:101], v[104:107], off sc1
	v_mul_f32_e32 v100, v20, v148
	v_fma_mix_f32 v56, v12, v56, v100 op_sel_hi:[0,1,0]
	v_cvt_f32_f16_sdwa v104, v52 dst_sel:DWORD dst_unused:UNUSED_PAD src0_sel:WORD_1
	s_waitcnt vmcnt(6)
	v_cvt_f32_f16_e32 v100, v116
	v_mul_f32_e32 v17, v20, v17
	v_fma_mix_f32 v17, v12, v48, v17 op_sel_hi:[0,1,0]
	v_cvt_f32_f16_e32 v57, v112
	v_cvt_f32_f16_sdwa v107, v112 dst_sel:DWORD dst_unused:UNUSED_PAD src0_sel:WORD_1
	v_fma_mix_f32 v17, v16, v40, v17 op_sel_hi:[0,1,0]
	v_mov_b32_e32 v131, v104
	v_mul_f32_e32 v17, v17, v100
	v_pk_mul_f32 v[100:101], v[82:83], v[130:131]
	v_fma_mix_f32 v56, v16, v52, v56 op_sel_hi:[0,1,0]
	v_fma_mix_f32 v100, v21, v48, v100 op_sel:[0,1,0] op_sel_hi:[0,1,0]
	v_add_f32_e32 v100, v100, v101
	v_mul_f32_e32 v106, v56, v57
	v_cvt_f32_f16_sdwa v105, v40 dst_sel:DWORD dst_unused:UNUSED_PAD src0_sel:WORD_1
	v_mul_f32_e32 v100, v100, v107
	v_cvt_pk_bf16_f32 v100, v106, v100
	v_cvt_f32_f16_e32 v106, v53
	v_lshlrev_b64 v[56:57], 13, v[102:103]
	v_pk_mul_f32 v[102:103], v[88:89], v[104:105]
	v_cvt_f32_f16_e32 v110, v113
	v_fma_mix_f32 v48, v13, v48, v102 op_sel:[0,1,0] op_sel_hi:[0,1,0]
	v_mov_b32_e32 v137, v106
	v_cvt_f32_f16_sdwa v111, v116 dst_sel:DWORD dst_unused:UNUSED_PAD src0_sel:WORD_1
	v_add_f32_e32 v48, v48, v103
	v_pk_mul_f32 v[102:103], v[80:81], v[136:137]
	v_cvt_f32_f16_e32 v107, v41
	v_fma_mix_f32 v101, v22, v49, v102 op_sel_hi:[0,1,0]
	v_add_f32_e32 v101, v101, v103
	v_mul_f32_e32 v101, v101, v110
	v_cvt_f32_f16_sdwa v110, v53 dst_sel:DWORD dst_unused:UNUSED_PAD src0_sel:WORD_1
	v_mul_f32_e32 v105, v48, v111
	v_cvt_f32_f16_e32 v48, v117
	v_pk_mul_f32 v[102:103], v[90:91], v[106:107]
	v_cvt_f32_f16_sdwa v112, v113 dst_sel:DWORD dst_unused:UNUSED_PAD src0_sel:WORD_1
	v_fma_mix_f32 v102, v14, v49, v102 op_sel_hi:[0,1,0]
	v_add_f32_e32 v102, v102, v103
	v_mov_b32_e32 v139, v110
	v_mul_f32_e32 v53, v102, v48
	v_pk_mul_f32 v[102:103], v[78:79], v[138:139]
	v_cvt_f32_f16_sdwa v111, v41 dst_sel:DWORD dst_unused:UNUSED_PAD src0_sel:WORD_1
	v_fma_mix_f32 v102, v23, v49, v102 op_sel:[0,1,0] op_sel_hi:[0,1,0]
	v_add_f32_e32 v102, v102, v103
	v_mul_f32_e32 v102, v102, v112
	v_cvt_f32_f16_e32 v112, v54
	v_cvt_f32_f16_sdwa v48, v117 dst_sel:DWORD dst_unused:UNUSED_PAD src0_sel:WORD_1
	v_cvt_pk_bf16_f32 v101, v101, v102
	v_pk_mul_f32 v[102:103], v[18:19], v[110:111]
	v_cvt_f32_f16_e32 v125, v114
	v_fma_mix_f32 v49, v15, v49, v102 op_sel:[0,1,0] op_sel_hi:[0,1,0]
	v_add_f32_e32 v49, v49, v103
	v_cvt_f32_f16_e32 v113, v42
	v_mov_b32_e32 v141, v112
	v_mul_f32_e32 v107, v49, v48
	v_pk_mul_f32 v[48:49], v[76:77], v[140:141]
	v_cvt_f32_f16_sdwa v126, v114 dst_sel:DWORD dst_unused:UNUSED_PAD src0_sel:WORD_1
	v_fma_mix_f32 v48, v8, v50, v48 op_sel_hi:[0,1,0]
	v_cvt_f32_f16_sdwa v114, v54 dst_sel:DWORD dst_unused:UNUSED_PAD src0_sel:WORD_1
	v_cvt_f32_f16_e32 v102, v118
	v_add_f32_e32 v48, v48, v49
	v_mul_f32_e32 v103, v48, v125
	v_pk_mul_f32 v[48:49], v[94:95], v[112:113]
	v_mov_b32_e32 v143, v114
; __device__ __forceinline__ void yb_phase(const Ptrs& P, int G, int tid) {
;     ...
;         for (int r = 0; r < 8; ++r) { pcv[r] = *(const h16x8*)(P.PP + (size_t)(t0 + r) * HW + c); ggv[r] = *(const h16x8*)(P.PGG + (size_t)(t0 + r) * HW + c); }
; #pragma unroll
;         for (int r = 0; r < 8; ++r) {
;             const h16x8 pc = pcv[r], gg = ggv[r];
;             float y[8];
; #pragma unroll
;             for (int j = 0; j < 8; ++j) { const float pcf = (float)pc[j]; y[j] = (float)gg[j] * (w0[j] * pm2[j] + w1[j] * pm1[j] + w2[j] * pcf); pm2[j] = pm1[j]; pm1[j] = pcf; }
;             u32x4 o; o.x = pkg(y[0], y[1]); o.y = pkg(y[2], y[3]); o.z = pkg(y[4], y[5]); o.w = pkg(y[6], y[7]);
;             *(u32x4*)(P.YAB + (size_t)(t0 + r) * D + HW + c) = o;
	v_fma_mix_f32 v48, v0, v50, v48 op_sel_hi:[0,1,0]
	v_add_f32_e32 v48, v48, v49
	v_cvt_f32_f16_e32 v127, v115
	v_cvt_f32_f16_sdwa v128, v115 dst_sel:DWORD dst_unused:UNUSED_PAD src0_sel:WORD_1
	v_mul_f32_e32 v111, v48, v102
	v_cvt_f32_f16_sdwa v115, v42 dst_sel:DWORD dst_unused:UNUSED_PAD src0_sel:WORD_1
	v_pk_mul_f32 v[48:49], v[74:75], v[142:143]
	v_cvt_f32_f16_e32 v116, v55
	v_fma_mix_f32 v48, v9, v50, v48 op_sel:[0,1,0] op_sel_hi:[0,1,0]
	v_add_f32_e32 v48, v48, v49
	v_cvt_f32_f16_sdwa v54, v118 dst_sel:DWORD dst_unused:UNUSED_PAD src0_sel:WORD_1
	v_mul_f32_e32 v48, v48, v126
	v_cvt_pk_bf16_f32 v102, v103, v48
	v_pk_mul_f32 v[48:49], v[4:5], v[114:115]
	v_cvt_f32_f16_e32 v117, v43
	v_fma_mix_f32 v48, v1, v50, v48 op_sel:[0,1,0] op_sel_hi:[0,1,0]
	v_add_f32_e32 v48, v48, v49
	v_mov_b32_e32 v125, v116
	v_mul_f32_e32 v50, v48, v54
	v_pk_mul_f32 v[48:49], v[72:73], v[124:125]
	v_cvt_f32_f16_sdwa v54, v55 dst_sel:DWORD dst_unused:UNUSED_PAD src0_sel:WORD_1
	v_fma_mix_f32 v48, v10, v51, v48 op_sel_hi:[0,1,0]
	v_cvt_f32_f16_e32 v103, v119
	v_add_f32_e32 v48, v48, v49
	v_mul_f32_e32 v113, v48, v127
	v_pk_mul_f32 v[48:49], v[92:93], v[116:117]
	v_mov_b32_e32 v145, v54
	v_fma_mix_f32 v48, v2, v51, v48 op_sel_hi:[0,1,0]
	v_add_f32_e32 v48, v48, v49
	v_mul_f32_e32 v115, v48, v103
	v_pk_mul_f32 v[48:49], v[70:71], v[144:145]
	v_lshl_add_u64 v[56:57], s[14:15], 0, v[56:57]
	v_fma_mix_f32 v48, v11, v51, v48 op_sel:[0,1,0] op_sel_hi:[0,1,0]
	v_cvt_f32_f16_sdwa v55, v43 dst_sel:DWORD dst_unused:UNUSED_PAD src0_sel:WORD_1
	v_add_f32_e32 v48, v48, v49
	v_lshl_add_u64 v[56:57], v[56:57], 0, v[66:67]
	v_mul_f32_e32 v48, v48, v128
	v_cvt_pk_bf16_f32 v103, v113, v48
	v_add_co_u32_e32 v48, vcc, s24, v56
	v_cvt_f32_f16_sdwa v117, v119 dst_sel:DWORD dst_unused:UNUSED_PAD src0_sel:WORD_1
	s_nop 0
	v_addc_co_u32_e32 v49, vcc, 0, v57, vcc
	v_lshlrev_b64 v[56:57], 13, v[98:99]
	global_store_dwordx4 v[48:49], v[100:103], off sc1
	v_pk_mul_f32 v[48:49], v[6:7], v[54:55]
	v_lshl_add_u64 v[56:57], s[14:15], 0, v[56:57]
	v_cvt_f32_f16_e32 v129, v40
	v_fma_mix_f32 v48, v3, v51, v48 op_sel:[0,1,0] op_sel_hi:[0,1,0]
	v_lshl_add_u64 v[56:57], v[56:57], 0, v[66:67]
	v_add_f32_e32 v48, v48, v49
	v_add_co_u32_e32 v56, vcc, s24, v56
	v_mul_f32_e32 v51, v48, v117
	v_cvt_pk_bf16_f32 v48, v17, v105
	s_nop 0
	v_addc_co_u32_e32 v57, vcc, 0, v57, vcc
	v_cvt_pk_bf16_f32 v49, v53, v107
	v_cvt_pk_bf16_f32 v50, v111, v50
	v_cvt_pk_bf16_f32 v51, v115, v51
	global_store_dwordx4 v[56:57], v[48:51], off sc1
	v_cvt_f32_f16_e32 v17, v36
	v_cvt_f32_f16_sdwa v56, v36 dst_sel:DWORD dst_unused:UNUSED_PAD src0_sel:WORD_1
	s_waitcnt vmcnt(7)
	v_cvt_f32_f16_e32 v48, v120
	v_mul_f32_e32 v49, v20, v129
	v_fma_mix_f32 v49, v12, v52, v49 op_sel_hi:[0,1,0]
	v_fma_mix_f32 v49, v16, v36, v49 op_sel_hi:[0,1,0]
	v_mul_f32_e32 v50, v49, v48
	v_lshlrev_b64 v[48:49], 13, v[96:97]
	v_lshl_add_u64 v[48:49], s[14:15], 0, v[48:49]
	v_lshl_add_u64 v[52:53], v[48:49], 0, v[66:67]
	s_waitcnt vmcnt(6)
	v_cvt_f32_f16_e32 v48, v62
	v_mul_f32_e32 v17, v20, v17
	v_fma_mix_f32 v17, v12, v40, v17 op_sel_hi:[0,1,0]
	v_cvt_f32_f16_sdwa v51, v120 dst_sel:DWORD dst_unused:UNUSED_PAD src0_sel:WORD_1
	v_fma_mix_f32 v17, v16, v24, v17 op_sel_hi:[0,1,0]
	v_mov_b32_e32 v105, v56
	v_mul_f32_e32 v17, v17, v48
	v_cvt_f32_f16_sdwa v57, v24 dst_sel:DWORD dst_unused:UNUSED_PAD src0_sel:WORD_1
	v_pk_mul_f32 v[48:49], v[82:83], v[104:105]
	v_cvt_f32_f16_e32 v96, v37
	v_fma_mix_f32 v48, v21, v40, v48 op_sel:[0,1,0] op_sel_hi:[0,1,0]
	v_add_f32_e32 v48, v48, v49
	v_cvt_f32_f16_sdwa v62, v62 dst_sel:DWORD dst_unused:UNUSED_PAD src0_sel:WORD_1
	v_mul_f32_e32 v48, v48, v51
	v_cvt_pk_bf16_f32 v48, v50, v48
	v_pk_mul_f32 v[50:51], v[88:89], v[56:57]
	v_cvt_f32_f16_e32 v97, v25
	v_fma_mix_f32 v40, v13, v40, v50 op_sel:[0,1,0] op_sel_hi:[0,1,0]
	v_add_f32_e32 v40, v40, v51
	v_mov_b32_e32 v107, v96
	v_mul_f32_e32 v57, v40, v62
	v_pk_mul_f32 v[50:51], v[80:81], v[106:107]
	v_cvt_f32_f16_sdwa v62, v37 dst_sel:DWORD dst_unused:UNUSED_PAD src0_sel:WORD_1
	v_cvt_f32_f16_e32 v40, v63
	v_fma_mix_f32 v49, v22, v41, v50 op_sel_hi:[0,1,0]
	v_add_f32_e32 v49, v49, v51
	v_pk_mul_f32 v[50:51], v[90:91], v[96:97]
	v_cvt_f32_f16_sdwa v98, v121 dst_sel:DWORD dst_unused:UNUSED_PAD src0_sel:WORD_1
	v_fma_mix_f32 v50, v14, v41, v50 op_sel_hi:[0,1,0]
	v_add_f32_e32 v50, v50, v51
	v_mov_b32_e32 v111, v62
	v_cvt_f32_f16_e32 v55, v121
	v_mul_f32_e32 v37, v50, v40
	v_pk_mul_f32 v[50:51], v[78:79], v[110:111]
	v_cvt_f32_f16_sdwa v40, v63 dst_sel:DWORD dst_unused:UNUSED_PAD src0_sel:WORD_1
	v_cvt_f32_f16_sdwa v63, v25 dst_sel:DWORD dst_unused:UNUSED_PAD src0_sel:WORD_1
	v_fma_mix_f32 v50, v23, v41, v50 op_sel:[0,1,0] op_sel_hi:[0,1,0]
	v_add_f32_e32 v50, v50, v51
	v_mul_f32_e32 v50, v50, v98
	v_cvt_f32_f16_e32 v98, v38
	v_mul_f32_e32 v49, v49, v55
	v_cvt_pk_bf16_f32 v49, v49, v50
	v_pk_mul_f32 v[50:51], v[18:19], v[62:63]
	v_cvt_f32_f16_e32 v100, v122
	v_fma_mix_f32 v41, v15, v41, v50 op_sel:[0,1,0] op_sel_hi:[0,1,0]
	v_add_f32_e32 v41, v41, v51
	v_mov_b32_e32 v113, v98
	v_mul_f32_e32 v63, v41, v40
	v_pk_mul_f32 v[40:41], v[76:77], v[112:113]
	v_cvt_f32_f16_e32 v99, v26
	v_fma_mix_f32 v40, v8, v42, v40 op_sel_hi:[0,1,0]
	v_add_f32_e32 v40, v40, v41
	v_mul_f32_e32 v51, v40, v100
	v_cvt_f32_f16_sdwa v100, v38 dst_sel:DWORD dst_unused:UNUSED_PAD src0_sel:WORD_1
	v_cvt_f32_f16_e32 v50, v64
	v_pk_mul_f32 v[40:41], v[94:95], v[98:99]
	v_cvt_f32_f16_sdwa v102, v122 dst_sel:DWORD dst_unused:UNUSED_PAD src0_sel:WORD_1
	v_fma_mix_f32 v40, v0, v42, v40 op_sel_hi:[0,1,0]
	v_add_f32_e32 v40, v40, v41
	v_mov_b32_e32 v115, v100
	v_mul_f32_e32 v97, v40, v50
	v_pk_mul_f32 v[40:41], v[74:75], v[114:115]
; __device__ __forceinline__ void yb_phase(const Ptrs& P, int G, int tid) {
;     ...
;         for (int r = 0; r < 8; ++r) { pcv[r] = *(const h16x8*)(P.PP + (size_t)(t0 + r) * HW + c); ggv[r] = *(const h16x8*)(P.PGG + (size_t)(t0 + r) * HW + c); }
; #pragma unroll
;         for (int r = 0; r < 8; ++r) {
;             const h16x8 pc = pcv[r], gg = ggv[r];
;             float y[8];
; #pragma unroll
;             for (int j = 0; j < 8; ++j) { const float pcf = (float)pc[j]; y[j] = (float)gg[j] * (w0[j] * pm2[j] + w1[j] * pm1[j] + w2[j] * pcf); pm2[j] = pm1[j]; pm1[j] = pcf; }
;             u32x4 o; o.x = pkg(y[0], y[1]); o.y = pkg(y[2], y[3]); o.z = pkg(y[4], y[5]); o.w = pkg(y[6], y[7]);
;             *(u32x4*)(P.YAB + (size_t)(t0 + r) * D + HW + c) = o;
	v_cvt_f32_f16_sdwa v101, v26 dst_sel:DWORD dst_unused:UNUSED_PAD src0_sel:WORD_1
	v_fma_mix_f32 v40, v9, v42, v40 op_sel:[0,1,0] op_sel_hi:[0,1,0]
	v_add_f32_e32 v40, v40, v41
	v_mul_f32_e32 v40, v40, v102
	v_cvt_f32_f16_e32 v102, v39
	v_cvt_f32_f16_sdwa v38, v64 dst_sel:DWORD dst_unused:UNUSED_PAD src0_sel:WORD_1
	v_cvt_pk_bf16_f32 v50, v51, v40
	v_pk_mul_f32 v[40:41], v[4:5], v[100:101]
	v_cvt_f32_f16_e32 v118, v123
	v_fma_mix_f32 v40, v1, v42, v40 op_sel:[0,1,0] op_sel_hi:[0,1,0]
	v_add_f32_e32 v40, v40, v41
	v_cvt_f32_f16_e32 v103, v27
	v_mov_b32_e32 v117, v102
	v_mul_f32_e32 v42, v40, v38
	v_pk_mul_f32 v[40:41], v[72:73], v[116:117]
	v_cvt_f32_f16_sdwa v64, v39 dst_sel:DWORD dst_unused:UNUSED_PAD src0_sel:WORD_1
	v_fma_mix_f32 v40, v10, v43, v40 op_sel_hi:[0,1,0]
	v_cvt_f32_f16_e32 v38, v65
	v_add_f32_e32 v40, v40, v41
	v_mul_f32_e32 v51, v40, v118
	v_pk_mul_f32 v[40:41], v[92:93], v[102:103]
	v_cvt_f32_f16_sdwa v119, v123 dst_sel:DWORD dst_unused:UNUSED_PAD src0_sel:WORD_1
	v_fma_mix_f32 v40, v2, v43, v40 op_sel_hi:[0,1,0]
	v_add_f32_e32 v40, v40, v41
	v_mov_b32_e32 v55, v64
	v_mul_f32_e32 v41, v40, v38
	v_pk_mul_f32 v[38:39], v[70:71], v[54:55]
	v_cvt_f32_f16_sdwa v40, v65 dst_sel:DWORD dst_unused:UNUSED_PAD src0_sel:WORD_1
	v_fma_mix_f32 v38, v11, v43, v38 op_sel:[0,1,0] op_sel_hi:[0,1,0]
	v_cvt_f32_f16_sdwa v65, v27 dst_sel:DWORD dst_unused:UNUSED_PAD src0_sel:WORD_1
	v_add_f32_e32 v38, v38, v39
	v_mul_f32_e32 v38, v38, v119
	v_cvt_pk_bf16_f32 v51, v51, v38
	v_add_co_u32_e32 v38, vcc, s24, v52
	v_cvt_f32_f16_e32 v120, v24
	s_nop 0
	v_addc_co_u32_e32 v39, vcc, 0, v53, vcc
	global_store_dwordx4 v[38:39], v[48:51], off sc1
	v_pk_mul_f32 v[38:39], v[6:7], v[64:65]
	s_nop 0
	v_fma_mix_f32 v38, v3, v43, v38 op_sel:[0,1,0] op_sel_hi:[0,1,0]
	v_add_f32_e32 v38, v38, v39
	v_mul_f32_e32 v43, v38, v40
	v_cvt_pk_bf16_f32 v40, v97, v42
	v_cvt_pk_bf16_f32 v41, v41, v43
	v_lshlrev_b64 v[42:43], 13, v[86:87]
	v_cvt_pk_bf16_f32 v38, v17, v57
	v_lshl_add_u64 v[42:43], s[14:15], 0, v[42:43]
	v_cvt_f32_f16_e32 v17, v32
	v_lshl_add_u64 v[42:43], v[42:43], 0, v[66:67]
	v_add_co_u32_e32 v42, vcc, s24, v42
	v_cvt_pk_bf16_f32 v39, v37, v63
	v_mul_f32_e32 v17, v20, v17
	s_nop 0
	v_addc_co_u32_e32 v43, vcc, 0, v43, vcc
	global_store_dwordx4 v[42:43], v[38:41], off sc1
	s_waitcnt vmcnt(7)
	v_cvt_f32_f16_e32 v42, v59
	v_cvt_f32_f16_sdwa v49, v60 dst_sel:DWORD dst_unused:UNUSED_PAD src0_sel:WORD_1
	v_mul_f32_e32 v38, v20, v120
	v_fma_mix_f32 v36, v12, v36, v38 op_sel_hi:[0,1,0]
	v_fma_mix_f32 v12, v12, v24, v17 op_sel_hi:[0,1,0]
	v_fma_mix_f32 v36, v16, v32, v36 op_sel_hi:[0,1,0]
	v_fma_mix_f32 v12, v16, v28, v12 op_sel_hi:[0,1,0]
	v_cvt_f32_f16_sdwa v16, v32 dst_sel:DWORD dst_unused:UNUSED_PAD src0_sel:WORD_1
	v_cvt_f32_f16_sdwa v17, v28 dst_sel:DWORD dst_unused:UNUSED_PAD src0_sel:WORD_1
	s_waitcnt vmcnt(6)
; __device__ __forceinline__ void yb_phase(const Ptrs& P, int G, int tid) {
;     ...
;         for (int r = 0; r < 8; ++r) { pcv[r] = *(const h16x8*)(P.PP + (size_t)(t0 + r) * HW + c); ggv[r] = *(const h16x8*)(P.PGG + (size_t)(t0 + r) * HW + c); }
; #pragma unroll
;         for (int r = 0; r < 8; ++r) {
;             const h16x8 pc = pcv[r], gg = ggv[r];
;             float y[8];
; #pragma unroll
;             for (int j = 0; j < 8; ++j) { const float pcf = (float)pc[j]; y[j] = (float)gg[j] * (w0[j] * pm2[j] + w1[j] * pm1[j] + w2[j] * pcf); pm2[j] = pm1[j]; pm1[j] = pcf; }
;             u32x4 o; o.x = pkg(y[0], y[1]); o.y = pkg(y[2], y[3]); o.z = pkg(y[4], y[5]); o.w = pkg(y[6], y[7]);
;             *(u32x4*)(P.YAB + (size_t)(t0 + r) * D + HW + c) = o;
;         }
;     }
	v_cvt_f32_f16_e32 v38, v44
	v_cvt_f32_f16_sdwa v20, v44 dst_sel:DWORD dst_unused:UNUSED_PAD src0_sel:WORD_1
	v_mov_b32_e32 v57, v16
	v_pk_mul_f32 v[16:17], v[88:89], v[16:17]
	v_mul_f32_e32 v32, v12, v38
	v_fma_mix_f32 v13, v13, v24, v16 op_sel:[0,1,0] op_sel_hi:[0,1,0]
	v_add_f32_e32 v13, v13, v17
	v_cvt_f32_f16_e32 v16, v33
	v_cvt_f32_f16_e32 v17, v29
	v_pk_mul_f32 v[38:39], v[82:83], v[56:57]
	v_cvt_f32_f16_e32 v48, v60
	v_mov_b32_e32 v97, v16
	v_pk_mul_f32 v[16:17], v[90:91], v[16:17]
	v_fma_mix_f32 v12, v21, v24, v38 op_sel:[0,1,0] op_sel_hi:[0,1,0]
	v_fma_mix_f32 v14, v14, v25, v16 op_sel_hi:[0,1,0]
	v_add_f32_e32 v14, v14, v17
	v_cvt_f32_f16_sdwa v16, v33 dst_sel:DWORD dst_unused:UNUSED_PAD src0_sel:WORD_1
	v_cvt_f32_f16_sdwa v17, v29 dst_sel:DWORD dst_unused:UNUSED_PAD src0_sel:WORD_1
	v_mul_f32_e32 v24, v13, v20
	v_cvt_f32_f16_e32 v13, v45
	v_mov_b32_e32 v63, v16
	v_pk_mul_f32 v[16:17], v[18:19], v[16:17]
	v_cvt_f32_f16_sdwa v33, v45 dst_sel:DWORD dst_unused:UNUSED_PAD src0_sel:WORD_1
	v_mul_f32_e32 v28, v14, v13
	v_fma_mix_f32 v14, v15, v25, v16 op_sel:[0,1,0] op_sel_hi:[0,1,0]
	v_add_f32_e32 v15, v14, v17
	v_cvt_f32_f16_e32 v14, v34
	v_mul_f32_e32 v18, v15, v33
	v_cvt_f32_f16_e32 v15, v30
	v_cvt_f32_f16_e32 v19, v46
	v_mov_b32_e32 v99, v14
	v_pk_mul_f32 v[16:17], v[76:77], v[98:99]
	v_pk_mul_f32 v[20:21], v[80:81], v[96:97]
	v_fma_mix_f32 v8, v8, v26, v16 op_sel_hi:[0,1,0]
	v_cvt_f32_f16_sdwa v16, v34 dst_sel:DWORD dst_unused:UNUSED_PAD src0_sel:WORD_1
	v_pk_mul_f32 v[14:15], v[94:95], v[14:15]
	v_fma_mix_f32 v20, v22, v25, v20 op_sel_hi:[0,1,0]
	v_add_f32_e32 v8, v8, v17
	v_fma_mix_f32 v0, v0, v26, v14 op_sel_hi:[0,1,0]
	v_cvt_f32_f16_sdwa v17, v30 dst_sel:DWORD dst_unused:UNUSED_PAD src0_sel:WORD_1
	v_mov_b32_e32 v101, v16
	v_add_f32_e32 v20, v20, v21
	v_add_f32_e32 v0, v0, v15
	v_pk_mul_f32 v[14:15], v[74:75], v[100:101]
	v_mul_f32_e32 v22, v20, v42
	v_pk_mul_f32 v[20:21], v[78:79], v[62:63]
	v_mul_f32_e32 v19, v0, v19
	v_fma_mix_f32 v0, v9, v26, v14 op_sel:[0,1,0] op_sel_hi:[0,1,0]
	v_fma_mix_f32 v13, v23, v25, v20 op_sel:[0,1,0] op_sel_hi:[0,1,0]
	v_cvt_f32_f16_sdwa v20, v46 dst_sel:DWORD dst_unused:UNUSED_PAD src0_sel:WORD_1
	v_add_f32_e32 v0, v0, v15
	v_mul_f32_e32 v0, v0, v49
	v_pk_mul_f32 v[4:5], v[4:5], v[16:17]
	v_mul_f32_e32 v8, v8, v48
	v_cvt_pk_bf16_f32 v14, v8, v0
	v_fma_mix_f32 v0, v1, v26, v4 op_sel:[0,1,0] op_sel_hi:[0,1,0]
	v_add_f32_e32 v1, v0, v5
	v_cvt_f32_f16_e32 v0, v35
	v_mul_f32_e32 v8, v1, v20
	v_cvt_f32_f16_e32 v1, v31
	v_cvt_f32_f16_e32 v50, v61
	v_mov_b32_e32 v103, v0
	v_cvt_f32_f16_e32 v37, v58
	v_pk_mul_f32 v[0:1], v[92:93], v[0:1]
	v_pk_mul_f32 v[4:5], v[72:73], v[102:103]
	v_fma_mix_f32 v0, v2, v27, v0 op_sel_hi:[0,1,0]
	v_add_f32_e32 v1, v0, v1
	v_cvt_f32_f16_sdwa v0, v35 dst_sel:DWORD dst_unused:UNUSED_PAD src0_sel:WORD_1
	v_fma_mix_f32 v4, v10, v27, v4 op_sel_hi:[0,1,0]
	v_cvt_f32_f16_sdwa v51, v61 dst_sel:DWORD dst_unused:UNUSED_PAD src0_sel:WORD_1
	v_add_f32_e32 v4, v4, v5
	v_mov_b32_e32 v65, v0
	v_mul_f32_e32 v10, v4, v50
	v_pk_mul_f32 v[4:5], v[70:71], v[64:65]
	v_mul_f32_e32 v40, v36, v37
	v_cvt_f32_f16_sdwa v41, v58 dst_sel:DWORD dst_unused:UNUSED_PAD src0_sel:WORD_1
	v_cvt_f32_f16_sdwa v43, v59 dst_sel:DWORD dst_unused:UNUSED_PAD src0_sel:WORD_1
	v_lshlrev_b64 v[36:37], 13, v[84:85]
	v_cvt_f32_f16_e32 v9, v47
	v_fma_mix_f32 v4, v11, v27, v4 op_sel:[0,1,0] op_sel_hi:[0,1,0]
	v_lshl_add_u64 v[36:37], s[14:15], 0, v[36:37]
	v_add_f32_e32 v4, v4, v5
	v_lshl_add_u64 v[36:37], v[36:37], 0, v[66:67]
	v_mul_f32_e32 v4, v4, v51
	v_add_f32_e32 v12, v12, v39
	v_add_f32_e32 v13, v13, v21
	v_cvt_pk_bf16_f32 v15, v10, v4
	v_add_co_u32_e32 v4, vcc, s24, v36
	v_mul_f32_e32 v12, v12, v41
	v_mul_f32_e32 v13, v13, v43
	v_mul_f32_e32 v9, v1, v9
	v_cvt_f32_f16_sdwa v1, v31 dst_sel:DWORD dst_unused:UNUSED_PAD src0_sel:WORD_1
	v_addc_co_u32_e32 v5, vcc, 0, v37, vcc
	v_cvt_pk_bf16_f32 v12, v40, v12
	v_cvt_pk_bf16_f32 v13, v22, v13
	global_store_dwordx4 v[4:5], v[12:15], off sc1
	v_lshlrev_b64 v[4:5], 13, v[68:69]
	v_lshl_add_u64 v[4:5], s[14:15], 0, v[4:5]
	v_cvt_f32_f16_sdwa v2, v47 dst_sel:DWORD dst_unused:UNUSED_PAD src0_sel:WORD_1
	v_lshl_add_u64 v[4:5], v[4:5], 0, v[66:67]
	v_pk_mul_f32 v[0:1], v[6:7], v[0:1]
	v_add_co_u32_e32 v4, vcc, 0x1000, v4
	v_fma_mix_f32 v0, v3, v27, v0 op_sel:[0,1,0] op_sel_hi:[0,1,0]
	s_nop 0
	v_addc_co_u32_e32 v5, vcc, 0, v5, vcc
	v_add_f32_e32 v0, v0, v1
	v_cmp_lt_i32_e32 vcc, s25, v108
	v_mul_f32_e32 v3, v0, v2
	s_or_b64 s[20:21], vcc, s[20:21]
	v_cvt_pk_bf16_f32 v0, v32, v24
	v_cvt_pk_bf16_f32 v1, v28, v18
	v_cvt_pk_bf16_f32 v2, v19, v8
	v_cvt_pk_bf16_f32 v3, v9, v3
	global_store_dwordx4 v[4:5], v[0:3], off sc1
	s_andn2_b64 exec, exec, s[20:21]
	s_cbranch_execz .LBB0_239

.LBB0_365:
	v_add_u32_e32 v4, v88, v113
	v_add_u32_e32 v8, v88, v107
	s_lshl_b64 s[56:57], s[58:59], 1
	ds_read_b128 v[4:7], v4
	ds_read_b128 v[8:11], v8
	s_add_u32 s56, s66, s56
	s_addc_u32 s57, s67, s57
	v_lshl_add_u64 v[14:15], s[56:57], 0, v[82:83]
	v_lshl_add_u64 v[12:13], s[56:57], 0, v[80:81]
	v_lshl_add_u64 v[14:15], v[14:15], 0, v[68:69]
	v_lshl_add_u64 v[12:13], v[12:13], 0, v[68:69]
	s_waitcnt lgkmcnt(1)
	global_store_dwordx4 v[14:15], v[4:7], off sc1
	s_waitcnt lgkmcnt(0)
	global_store_dwordx4 v[12:13], v[8:11], off sc1

; #define H3_FLUSH() do { _Pragma("unroll") for (int rep = 0; rep < 2; ++rep) { const int cidx = tid + 512 * rep; \
;         *(u32x4*)((unsigned short*)P.YAB + yoff + (size_t)(cidx >> 4) * D + (cidx & 15) * 8) = *(const LAS u32x4*)(YST + (cidx >> 4) * 128 + (cidx & 15) * 8); } } while (0)
; __device__ __forceinline__ void h3_phase(const Ptrs& P, LAS unsigned char* lds, int bx, int G, int tid) {
;     ...
;     __syncthreads();
;     if (have_y) H3_FLUSH();
.LBB0_404:
	v_add_u32_e32 v0, v88, v113
	s_waitcnt lgkmcnt(0)
	s_barrier
	ds_read_b128 v[0:3], v0
	s_lshl_b64 s[0:1], s[58:59], 1
	s_add_u32 s0, s66, s0
	v_add_u32_e32 v4, v88, v107
	s_addc_u32 s1, s67, s1
	ds_read_b128 v[4:7], v4
	v_lshl_add_u64 v[8:9], s[0:1], 0, v[82:83]
	v_mov_b32_e32 v69, 0
	v_lshl_add_u64 v[8:9], v[8:9], 0, v[68:69]
	s_waitcnt lgkmcnt(1)
	global_store_dwordx4 v[8:9], v[0:3], off sc1
	s_nop 1
	v_lshl_add_u64 v[0:1], s[0:1], 0, v[80:81]
	v_lshl_add_u64 v[0:1], v[0:1], 0, v[68:69]
	s_waitcnt lgkmcnt(0)
	global_store_dwordx4 v[0:1], v[4:7], off sc1
